# no setprio plus the pads between consecutive LDS-DMA issue blocks removed
# baseline (speedup 1.0000x reference)
.Lnb_p1:
	s_add_i32 s7, s4, 0xfff84000
	s_cmp_eq_u32 s6, 28
	s_cselect_b32 s17, s0, s7
	s_cselect_b32 s16, s1, s5
	s_or_b32 s7, s17, 0x4000
	s_mov_b32 m0, s79
	s_nop 0
	buffer_load_dwordx4 v242, s[24:27], s4 offen lds
	s_mov_b32 m0, s83
	s_nop 0
	buffer_load_dwordx4 v243, s[24:27], s4 offen lds
	s_waitcnt vmcnt(24)
	s_waitcnt lgkmcnt(0)
	s_barrier
	s_waitcnt lgkmcnt(7)
	v_mfma_f32_16x16x32_bf16 v[180:183], v[16:19], v[192:195], 0
	v_mfma_f32_16x16x32_bf16 v[164:167], v[24:27], v[192:195], 0
	s_waitcnt lgkmcnt(5)
	v_mfma_f32_16x16x32_bf16 v[148:151], v[16:19], v[200:203], 0
	v_mfma_f32_16x16x32_bf16 v[140:143], v[24:27], v[200:203], 0
	s_waitcnt lgkmcnt(3)
	v_mfma_f32_16x16x32_bf16 v[132:135], v[16:19], v[220:223], 0
	v_mfma_f32_16x16x32_bf16 v[124:127], v[24:27], v[220:223], 0
	s_waitcnt lgkmcnt(1)
	v_mfma_f32_16x16x32_bf16 v[116:119], v[16:19], v[228:231], 0
	v_mfma_f32_16x16x32_bf16 v[108:111], v[24:27], v[228:231], 0
	v_mfma_f32_16x16x32_bf16 v[180:183], v[20:23], v[196:199], v[180:183]
	v_mfma_f32_16x16x32_bf16 v[164:167], v[28:31], v[196:199], v[164:167]
	v_mfma_f32_16x16x32_bf16 v[148:151], v[20:23], v[204:207], v[148:151]
	v_mfma_f32_16x16x32_bf16 v[140:143], v[28:31], v[204:207], v[140:143]
	v_mfma_f32_16x16x32_bf16 v[132:135], v[20:23], v[224:227], v[132:135]
	v_mfma_f32_16x16x32_bf16 v[124:127], v[28:31], v[224:227], v[124:127]
	s_waitcnt lgkmcnt(0)
	v_mfma_f32_16x16x32_bf16 v[116:119], v[20:23], v[246:249], v[116:119]
	v_mfma_f32_16x16x32_bf16 v[108:111], v[28:31], v[246:249], v[108:111]
	v_mfma_f32_16x16x32_bf16 v[172:175], v[152:155], v[192:195], 0
	v_mfma_f32_16x16x32_bf16 v[156:159], v[168:171], v[192:195], 0
	v_mfma_f32_16x16x32_bf16 v[144:147], v[152:155], v[200:203], 0
	v_mfma_f32_16x16x32_bf16 v[136:139], v[168:171], v[200:203], 0
	v_mfma_f32_16x16x32_bf16 v[128:131], v[152:155], v[220:223], 0
	v_mfma_f32_16x16x32_bf16 v[120:123], v[168:171], v[220:223], 0
	v_mfma_f32_16x16x32_bf16 v[112:115], v[152:155], v[228:231], 0
	v_mfma_f32_16x16x32_bf16 v[104:107], v[168:171], v[228:231], 0
	v_mfma_f32_16x16x32_bf16 v[172:175], v[160:163], v[196:199], v[172:175]
	v_mfma_f32_16x16x32_bf16 v[156:159], v[176:179], v[196:199], v[156:159]
	v_mfma_f32_16x16x32_bf16 v[144:147], v[160:163], v[204:207], v[144:147]
	v_mfma_f32_16x16x32_bf16 v[136:139], v[176:179], v[204:207], v[136:139]
	v_mfma_f32_16x16x32_bf16 v[128:131], v[160:163], v[224:227], v[128:131]
	v_mfma_f32_16x16x32_bf16 v[120:123], v[176:179], v[224:227], v[120:123]
	v_mfma_f32_16x16x32_bf16 v[112:115], v[160:163], v[246:249], v[112:115]
	v_mfma_f32_16x16x32_bf16 v[104:107], v[176:179], v[246:249], v[104:107]
	s_barrier
	ds_read_b128 v[192:195], v245 offset:16384
	ds_read_b128 v[196:199], v245 offset:17408
	ds_read_b128 v[200:203], v245 offset:18432
	ds_read_b128 v[204:207], v245 offset:19456
	ds_read_b128 v[220:223], v245 offset:20480
	ds_read_b128 v[224:227], v245 offset:21504
	ds_read_b128 v[228:231], v245 offset:22528
	ds_read_b128 v[246:249], v245 offset:23552
	s_mov_b32 m0, s51
	s_nop 0
	buffer_load_dwordx4 v242, s[56:59], s16 offen lds
	s_add_i32 s18, s16, 0x80000
	s_mov_b32 m0, s52
	s_nop 0
	buffer_load_dwordx4 v243, s[56:59], s16 offen lds
	s_mov_b32 m0, s53
	s_nop 0
	buffer_load_dwordx4 v242, s[56:59], s18 offen lds
	s_mov_b32 m0, s55
	s_nop 0
	buffer_load_dwordx4 v243, s[56:59], s18 offen lds
	s_mov_b32 m0, s31
	s_nop 0
	buffer_load_dwordx4 v242, s[24:27], s17 offen lds
	s_mov_b32 m0, s68
	s_nop 0
	buffer_load_dwordx4 v243, s[24:27], s17 offen lds
	s_waitcnt vmcnt(24)
	s_waitcnt lgkmcnt(0)
	s_barrier
	s_waitcnt lgkmcnt(7)
	v_mfma_f32_16x16x32_bf16 v[76:79], v[16:19], v[192:195], 0
	v_mfma_f32_16x16x32_bf16 v[68:71], v[24:27], v[192:195], 0
	s_waitcnt lgkmcnt(5)
	v_mfma_f32_16x16x32_bf16 v[60:63], v[16:19], v[200:203], 0
	v_mfma_f32_16x16x32_bf16 v[52:55], v[24:27], v[200:203], 0
	s_waitcnt lgkmcnt(3)
	v_mfma_f32_16x16x32_bf16 v[44:47], v[16:19], v[220:223], 0
	v_mfma_f32_16x16x32_bf16 v[36:39], v[24:27], v[220:223], 0
	s_waitcnt lgkmcnt(1)
	v_mfma_f32_16x16x32_bf16 v[12:15], v[16:19], v[228:231], 0
	v_mfma_f32_16x16x32_bf16 v[4:7], v[24:27], v[228:231], 0
	v_mfma_f32_16x16x32_bf16 v[76:79], v[20:23], v[196:199], v[76:79]
	v_mfma_f32_16x16x32_bf16 v[68:71], v[28:31], v[196:199], v[68:71]
	v_mfma_f32_16x16x32_bf16 v[60:63], v[20:23], v[204:207], v[60:63]
	v_mfma_f32_16x16x32_bf16 v[52:55], v[28:31], v[204:207], v[52:55]
	v_mfma_f32_16x16x32_bf16 v[44:47], v[20:23], v[224:227], v[44:47]
	v_mfma_f32_16x16x32_bf16 v[36:39], v[28:31], v[224:227], v[36:39]
	s_waitcnt lgkmcnt(0)
	v_mfma_f32_16x16x32_bf16 v[12:15], v[20:23], v[246:249], v[12:15]
	v_mfma_f32_16x16x32_bf16 v[4:7], v[28:31], v[246:249], v[4:7]
	v_mfma_f32_16x16x32_bf16 v[40:43], v[152:155], v[220:223], 0
	v_mfma_f32_16x16x32_bf16 v[32:35], v[168:171], v[220:223], 0
	v_mfma_f32_16x16x32_bf16 v[8:11], v[152:155], v[228:231], 0
	v_mfma_f32_16x16x32_bf16 v[0:3], v[168:171], v[228:231], 0
	v_mfma_f32_16x16x32_bf16 v[16:19], v[152:155], v[192:195], 0
	v_mfma_f32_16x16x32_bf16 v[20:23], v[168:171], v[192:195], 0
	v_mfma_f32_16x16x32_bf16 v[24:27], v[152:155], v[200:203], 0
	v_mfma_f32_16x16x32_bf16 v[28:31], v[168:171], v[200:203], 0
	v_mfma_f32_16x16x32_bf16 v[40:43], v[160:163], v[224:227], v[40:43]
	v_mfma_f32_16x16x32_bf16 v[32:35], v[176:179], v[224:227], v[32:35]
	v_mfma_f32_16x16x32_bf16 v[8:11], v[160:163], v[246:249], v[8:11]
	v_mfma_f32_16x16x32_bf16 v[0:3], v[176:179], v[246:249], v[0:3]
	v_mfma_f32_16x16x32_bf16 v[16:19], v[160:163], v[196:199], v[16:19]
	v_mfma_f32_16x16x32_bf16 v[20:23], v[176:179], v[196:199], v[20:23]
	v_mfma_f32_16x16x32_bf16 v[24:27], v[160:163], v[204:207], v[24:27]
	v_mfma_f32_16x16x32_bf16 v[28:31], v[176:179], v[204:207], v[28:31]
	s_barrier
	v_add_u32_e32 v72, 0x18000, v83
	v_add_u32_e32 v80, 0x1c000, v83
	ds_read_b128 v[48:51], v72
	ds_read_b128 v[56:59], v72 offset:1024
	ds_read_b128 v[64:67], v72 offset:2048
	ds_read_b128 v[72:75], v72 offset:3072
	ds_read_b128 v[152:155], v80
	ds_read_b128 v[160:163], v80 offset:1024
	ds_read_b128 v[168:171], v80 offset:2048
	ds_read_b128 v[176:179], v80 offset:3072
	ds_read_b128 v[192:195], v245 offset:32768
	ds_read_b128 v[196:199], v245 offset:33792
	ds_read_b128 v[200:203], v245 offset:34816
	ds_read_b128 v[204:207], v245 offset:35840
	ds_read_b128 v[220:223], v245 offset:36864
	ds_read_b128 v[224:227], v245 offset:37888
	ds_read_b128 v[228:231], v245 offset:38912
	ds_read_b128 v[246:249], v245 offset:39936
	s_add_i32 s17, s17, 0x80000
	s_mov_b32 m0, s69
	s_nop 0
	buffer_load_dwordx4 v242, s[24:27], s17 offen lds
	s_mov_b32 m0, s70
	s_nop 0
	buffer_load_dwordx4 v243, s[24:27], s17 offen lds
	s_waitcnt vmcnt(8)
	s_waitcnt lgkmcnt(0)
	s_barrier
	s_waitcnt lgkmcnt(7)
	v_mfma_f32_16x16x32_bf16 v[180:183], v[48:51], v[192:195], v[180:183]
	v_mfma_f32_16x16x32_bf16 v[164:167], v[64:67], v[192:195], v[164:167]
	s_waitcnt lgkmcnt(5)
	v_mfma_f32_16x16x32_bf16 v[148:151], v[48:51], v[200:203], v[148:151]
	v_mfma_f32_16x16x32_bf16 v[140:143], v[64:67], v[200:203], v[140:143]
	s_waitcnt lgkmcnt(3)
	v_mfma_f32_16x16x32_bf16 v[132:135], v[48:51], v[220:223], v[132:135]
	v_mfma_f32_16x16x32_bf16 v[124:127], v[64:67], v[220:223], v[124:127]
	s_waitcnt lgkmcnt(1)
	v_mfma_f32_16x16x32_bf16 v[116:119], v[48:51], v[228:231], v[116:119]
	v_mfma_f32_16x16x32_bf16 v[108:111], v[64:67], v[228:231], v[108:111]
	v_mfma_f32_16x16x32_bf16 v[180:183], v[56:59], v[196:199], v[180:183]
	v_mfma_f32_16x16x32_bf16 v[164:167], v[72:75], v[196:199], v[164:167]
	v_mfma_f32_16x16x32_bf16 v[148:151], v[56:59], v[204:207], v[148:151]
	v_mfma_f32_16x16x32_bf16 v[140:143], v[72:75], v[204:207], v[140:143]
	v_mfma_f32_16x16x32_bf16 v[132:135], v[56:59], v[224:227], v[132:135]
	v_mfma_f32_16x16x32_bf16 v[124:127], v[72:75], v[224:227], v[124:127]
	s_waitcnt lgkmcnt(0)
	v_mfma_f32_16x16x32_bf16 v[116:119], v[56:59], v[246:249], v[116:119]
	v_mfma_f32_16x16x32_bf16 v[108:111], v[72:75], v[246:249], v[108:111]
	v_mfma_f32_16x16x32_bf16 v[172:175], v[152:155], v[192:195], v[172:175]
	v_mfma_f32_16x16x32_bf16 v[156:159], v[168:171], v[192:195], v[156:159]
	v_mfma_f32_16x16x32_bf16 v[144:147], v[152:155], v[200:203], v[144:147]
	v_mfma_f32_16x16x32_bf16 v[136:139], v[168:171], v[200:203], v[136:139]
	v_mfma_f32_16x16x32_bf16 v[128:131], v[152:155], v[220:223], v[128:131]
	v_mfma_f32_16x16x32_bf16 v[120:123], v[168:171], v[220:223], v[120:123]
	v_mfma_f32_16x16x32_bf16 v[112:115], v[152:155], v[228:231], v[112:115]
	v_mfma_f32_16x16x32_bf16 v[104:107], v[168:171], v[228:231], v[104:107]
	v_mfma_f32_16x16x32_bf16 v[172:175], v[160:163], v[196:199], v[172:175]
	v_mfma_f32_16x16x32_bf16 v[156:159], v[176:179], v[196:199], v[156:159]
	v_mfma_f32_16x16x32_bf16 v[144:147], v[160:163], v[204:207], v[144:147]
	v_mfma_f32_16x16x32_bf16 v[136:139], v[176:179], v[204:207], v[136:139]
	v_mfma_f32_16x16x32_bf16 v[128:131], v[160:163], v[224:227], v[128:131]
	v_mfma_f32_16x16x32_bf16 v[120:123], v[176:179], v[224:227], v[120:123]
	v_mfma_f32_16x16x32_bf16 v[112:115], v[160:163], v[246:249], v[112:115]
	v_mfma_f32_16x16x32_bf16 v[104:107], v[176:179], v[246:249], v[104:107]
	s_barrier
	ds_read_b128 v[192:195], v245 offset:49152
	ds_read_b128 v[196:199], v245 offset:50176
	ds_read_b128 v[200:203], v245 offset:51200
	ds_read_b128 v[204:207], v245 offset:52224
	ds_read_b128 v[220:223], v245 offset:53248
	ds_read_b128 v[224:227], v245 offset:54272
	ds_read_b128 v[228:231], v245 offset:55296
	ds_read_b128 v[246:249], v245 offset:56320
	s_or_b32 s17, s16, 0x4000
	s_mov_b32 m0, s73
	s_nop 0
	buffer_load_dwordx4 v242, s[56:59], s17 offen lds
	s_add_i32 s16, s16, 0x84000
	s_mov_b32 m0, s74
	s_nop 0
	buffer_load_dwordx4 v243, s[56:59], s17 offen lds
	s_mov_b32 m0, s77
	s_nop 0
	buffer_load_dwordx4 v242, s[56:59], s16 offen lds
	s_mov_b32 m0, s78
	s_nop 0
	buffer_load_dwordx4 v243, s[56:59], s16 offen lds
	s_mov_b32 m0, s75
	s_nop 0
	buffer_load_dwordx4 v242, s[24:27], s7 offen lds
	s_mov_b32 m0, s76
	s_nop 0
	buffer_load_dwordx4 v243, s[24:27], s7 offen lds
	s_waitcnt vmcnt(8)
	s_waitcnt lgkmcnt(0)
	s_barrier
	s_waitcnt lgkmcnt(7)
	v_mfma_f32_16x16x32_bf16 v[76:79], v[48:51], v[192:195], v[76:79]
	v_mfma_f32_16x16x32_bf16 v[68:71], v[64:67], v[192:195], v[68:71]
	s_waitcnt lgkmcnt(5)
	v_mfma_f32_16x16x32_bf16 v[60:63], v[48:51], v[200:203], v[60:63]
	v_mfma_f32_16x16x32_bf16 v[52:55], v[64:67], v[200:203], v[52:55]
	s_waitcnt lgkmcnt(3)
	v_mfma_f32_16x16x32_bf16 v[44:47], v[48:51], v[220:223], v[44:47]
	v_mfma_f32_16x16x32_bf16 v[36:39], v[64:67], v[220:223], v[36:39]
	s_waitcnt lgkmcnt(1)
	v_mfma_f32_16x16x32_bf16 v[12:15], v[48:51], v[228:231], v[12:15]
	v_mfma_f32_16x16x32_bf16 v[4:7], v[64:67], v[228:231], v[4:7]
	v_mfma_f32_16x16x32_bf16 v[76:79], v[56:59], v[196:199], v[76:79]
	v_mfma_f32_16x16x32_bf16 v[68:71], v[72:75], v[196:199], v[68:71]
	v_mfma_f32_16x16x32_bf16 v[60:63], v[56:59], v[204:207], v[60:63]
	v_mfma_f32_16x16x32_bf16 v[52:55], v[72:75], v[204:207], v[52:55]
	v_mfma_f32_16x16x32_bf16 v[44:47], v[56:59], v[224:227], v[44:47]
	v_mfma_f32_16x16x32_bf16 v[36:39], v[72:75], v[224:227], v[36:39]
	s_waitcnt lgkmcnt(0)
	v_mfma_f32_16x16x32_bf16 v[12:15], v[56:59], v[246:249], v[12:15]
	v_mfma_f32_16x16x32_bf16 v[4:7], v[72:75], v[246:249], v[4:7]
	v_mfma_f32_16x16x32_bf16 v[16:19], v[152:155], v[192:195], v[16:19]
	v_mfma_f32_16x16x32_bf16 v[72:75], v[160:163], v[196:199], v[16:19]
	v_mfma_f32_16x16x32_bf16 v[16:19], v[168:171], v[192:195], v[20:23]
	v_mfma_f32_16x16x32_bf16 v[64:67], v[176:179], v[196:199], v[16:19]
	v_mfma_f32_16x16x32_bf16 v[16:19], v[152:155], v[200:203], v[24:27]
	v_mfma_f32_16x16x32_bf16 v[56:59], v[160:163], v[204:207], v[16:19]
	v_mfma_f32_16x16x32_bf16 v[16:19], v[168:171], v[200:203], v[28:31]
	v_mfma_f32_16x16x32_bf16 v[48:51], v[176:179], v[204:207], v[16:19]
	v_mfma_f32_16x16x32_bf16 v[16:19], v[152:155], v[220:223], v[40:43]
	v_mfma_f32_16x16x32_bf16 v[40:43], v[160:163], v[224:227], v[16:19]
	v_mfma_f32_16x16x32_bf16 v[16:19], v[168:171], v[220:223], v[32:35]
	v_mfma_f32_16x16x32_bf16 v[8:11], v[152:155], v[228:231], v[8:11]
	v_mfma_f32_16x16x32_bf16 v[0:3], v[168:171], v[228:231], v[0:3]
	v_mfma_f32_16x16x32_bf16 v[32:35], v[176:179], v[224:227], v[16:19]
	v_mfma_f32_16x16x32_bf16 v[8:11], v[160:163], v[246:249], v[8:11]
	v_mfma_f32_16x16x32_bf16 v[0:3], v[176:179], v[246:249], v[0:3]
	s_barrier
	s_add_i32 s6, s6, 2
	s_add_i32 s4, s4, 0x8000
	s_add_i32 s5, s5, 0x8000
.LBB0_143:
	v_add_u32_e32 v28, 0x10000, v83
	v_add_u32_e32 v80, 0x14000, v83
	ds_read_b128 v[16:19], v28
	ds_read_b128 v[20:23], v28 offset:1024
	ds_read_b128 v[24:27], v28 offset:2048
	ds_read_b128 v[28:31], v28 offset:3072
	ds_read_b128 v[152:155], v80
	ds_read_b128 v[160:163], v80 offset:1024
	ds_read_b128 v[168:171], v80 offset:2048
	ds_read_b128 v[176:179], v80 offset:3072
	s_add_i32 s7, s4, 0xfff84000
	s_cmp_eq_u32 s6, 28
	s_cselect_b32 s17, s0, s7
	s_cselect_b32 s16, s1, s5
	s_or_b32 s7, s17, 0x4000
	ds_read_b128 v[192:195], v245
	ds_read_b128 v[196:199], v245 offset:1024
	ds_read_b128 v[200:203], v245 offset:2048
	ds_read_b128 v[204:207], v245 offset:3072
	ds_read_b128 v[220:223], v245 offset:4096
	ds_read_b128 v[224:227], v245 offset:5120
	ds_read_b128 v[228:231], v245 offset:6144
	ds_read_b128 v[246:249], v245 offset:7168
	s_mov_b32 m0, s79
	s_nop 0
	buffer_load_dwordx4 v242, s[24:27], s4 offen lds
	s_mov_b32 m0, s83
	s_nop 0
	buffer_load_dwordx4 v243, s[24:27], s4 offen lds
	s_waitcnt vmcnt(8)
	s_waitcnt lgkmcnt(0)
	s_barrier
	s_waitcnt lgkmcnt(7)
	v_mfma_f32_16x16x32_bf16 v[180:183], v[16:19], v[192:195], v[180:183]
	v_mfma_f32_16x16x32_bf16 v[164:167], v[24:27], v[192:195], v[164:167]
	s_waitcnt lgkmcnt(5)
	v_mfma_f32_16x16x32_bf16 v[148:151], v[16:19], v[200:203], v[148:151]
	v_mfma_f32_16x16x32_bf16 v[140:143], v[24:27], v[200:203], v[140:143]
	s_waitcnt lgkmcnt(3)
	v_mfma_f32_16x16x32_bf16 v[132:135], v[16:19], v[220:223], v[132:135]
	v_mfma_f32_16x16x32_bf16 v[124:127], v[24:27], v[220:223], v[124:127]
	s_waitcnt lgkmcnt(1)
	v_mfma_f32_16x16x32_bf16 v[116:119], v[16:19], v[228:231], v[116:119]
	v_mfma_f32_16x16x32_bf16 v[108:111], v[24:27], v[228:231], v[108:111]
	v_mfma_f32_16x16x32_bf16 v[180:183], v[20:23], v[196:199], v[180:183]
	v_mfma_f32_16x16x32_bf16 v[164:167], v[28:31], v[196:199], v[164:167]
	v_mfma_f32_16x16x32_bf16 v[148:151], v[20:23], v[204:207], v[148:151]
	v_mfma_f32_16x16x32_bf16 v[140:143], v[28:31], v[204:207], v[140:143]
	v_mfma_f32_16x16x32_bf16 v[132:135], v[20:23], v[224:227], v[132:135]
	v_mfma_f32_16x16x32_bf16 v[124:127], v[28:31], v[224:227], v[124:127]
	s_waitcnt lgkmcnt(0)
	v_mfma_f32_16x16x32_bf16 v[116:119], v[20:23], v[246:249], v[116:119]
	v_mfma_f32_16x16x32_bf16 v[108:111], v[28:31], v[246:249], v[108:111]
	v_mfma_f32_16x16x32_bf16 v[172:175], v[152:155], v[192:195], v[172:175]
	v_mfma_f32_16x16x32_bf16 v[156:159], v[168:171], v[192:195], v[156:159]
	v_mfma_f32_16x16x32_bf16 v[144:147], v[152:155], v[200:203], v[144:147]
	v_mfma_f32_16x16x32_bf16 v[136:139], v[168:171], v[200:203], v[136:139]
	v_mfma_f32_16x16x32_bf16 v[128:131], v[152:155], v[220:223], v[128:131]
	v_mfma_f32_16x16x32_bf16 v[120:123], v[168:171], v[220:223], v[120:123]
	v_mfma_f32_16x16x32_bf16 v[112:115], v[152:155], v[228:231], v[112:115]
	v_mfma_f32_16x16x32_bf16 v[104:107], v[168:171], v[228:231], v[104:107]
	v_mfma_f32_16x16x32_bf16 v[172:175], v[160:163], v[196:199], v[172:175]
	v_mfma_f32_16x16x32_bf16 v[156:159], v[176:179], v[196:199], v[156:159]
	v_mfma_f32_16x16x32_bf16 v[144:147], v[160:163], v[204:207], v[144:147]
	v_mfma_f32_16x16x32_bf16 v[136:139], v[176:179], v[204:207], v[136:139]
	v_mfma_f32_16x16x32_bf16 v[128:131], v[160:163], v[224:227], v[128:131]
	v_mfma_f32_16x16x32_bf16 v[120:123], v[176:179], v[224:227], v[120:123]
	v_mfma_f32_16x16x32_bf16 v[112:115], v[160:163], v[246:249], v[112:115]
	v_mfma_f32_16x16x32_bf16 v[104:107], v[176:179], v[246:249], v[104:107]
	s_barrier
	ds_read_b128 v[192:195], v245 offset:16384
	ds_read_b128 v[196:199], v245 offset:17408
	ds_read_b128 v[200:203], v245 offset:18432
	ds_read_b128 v[204:207], v245 offset:19456
	ds_read_b128 v[220:223], v245 offset:20480
	ds_read_b128 v[224:227], v245 offset:21504
	ds_read_b128 v[228:231], v245 offset:22528
	ds_read_b128 v[246:249], v245 offset:23552
	s_mov_b32 m0, s51
	s_nop 0
	buffer_load_dwordx4 v242, s[56:59], s16 offen lds
	s_add_i32 s18, s16, 0x80000
	s_mov_b32 m0, s52
	s_nop 0
	buffer_load_dwordx4 v243, s[56:59], s16 offen lds
	s_mov_b32 m0, s53
	s_nop 0
	buffer_load_dwordx4 v242, s[56:59], s18 offen lds
	s_mov_b32 m0, s55
	s_nop 0
	buffer_load_dwordx4 v243, s[56:59], s18 offen lds
	s_mov_b32 m0, s31
	s_nop 0
	buffer_load_dwordx4 v242, s[24:27], s17 offen lds
	s_mov_b32 m0, s68
	s_nop 0
	buffer_load_dwordx4 v243, s[24:27], s17 offen lds
	s_waitcnt vmcnt(8)
	s_waitcnt lgkmcnt(0)
	s_barrier
	s_waitcnt lgkmcnt(7)
	v_mfma_f32_16x16x32_bf16 v[76:79], v[16:19], v[192:195], v[76:79]
	v_mfma_f32_16x16x32_bf16 v[68:71], v[24:27], v[192:195], v[68:71]
	s_waitcnt lgkmcnt(5)
	v_mfma_f32_16x16x32_bf16 v[60:63], v[16:19], v[200:203], v[60:63]
	v_mfma_f32_16x16x32_bf16 v[52:55], v[24:27], v[200:203], v[52:55]
	s_waitcnt lgkmcnt(3)
	v_mfma_f32_16x16x32_bf16 v[44:47], v[16:19], v[220:223], v[44:47]
	v_mfma_f32_16x16x32_bf16 v[36:39], v[24:27], v[220:223], v[36:39]
	s_waitcnt lgkmcnt(1)
	v_mfma_f32_16x16x32_bf16 v[12:15], v[16:19], v[228:231], v[12:15]
	v_mfma_f32_16x16x32_bf16 v[4:7], v[24:27], v[228:231], v[4:7]
	v_mfma_f32_16x16x32_bf16 v[76:79], v[20:23], v[196:199], v[76:79]
	v_mfma_f32_16x16x32_bf16 v[68:71], v[28:31], v[196:199], v[68:71]
	v_mfma_f32_16x16x32_bf16 v[60:63], v[20:23], v[204:207], v[60:63]
	v_mfma_f32_16x16x32_bf16 v[52:55], v[28:31], v[204:207], v[52:55]
	v_mfma_f32_16x16x32_bf16 v[44:47], v[20:23], v[224:227], v[44:47]
	v_mfma_f32_16x16x32_bf16 v[36:39], v[28:31], v[224:227], v[36:39]
	s_waitcnt lgkmcnt(0)
	v_mfma_f32_16x16x32_bf16 v[12:15], v[20:23], v[246:249], v[12:15]
	v_mfma_f32_16x16x32_bf16 v[4:7], v[28:31], v[246:249], v[4:7]
	v_mfma_f32_16x16x32_bf16 v[40:43], v[152:155], v[220:223], v[40:43]
	v_mfma_f32_16x16x32_bf16 v[32:35], v[168:171], v[220:223], v[32:35]
	v_mfma_f32_16x16x32_bf16 v[8:11], v[152:155], v[228:231], v[8:11]
	v_mfma_f32_16x16x32_bf16 v[0:3], v[168:171], v[228:231], v[0:3]
	v_mfma_f32_16x16x32_bf16 v[16:19], v[152:155], v[192:195], v[72:75]
	v_mfma_f32_16x16x32_bf16 v[20:23], v[168:171], v[192:195], v[64:67]
	v_mfma_f32_16x16x32_bf16 v[24:27], v[152:155], v[200:203], v[56:59]
	v_mfma_f32_16x16x32_bf16 v[28:31], v[168:171], v[200:203], v[48:51]
	v_mfma_f32_16x16x32_bf16 v[40:43], v[160:163], v[224:227], v[40:43]
	v_mfma_f32_16x16x32_bf16 v[32:35], v[176:179], v[224:227], v[32:35]
	v_mfma_f32_16x16x32_bf16 v[8:11], v[160:163], v[246:249], v[8:11]
	v_mfma_f32_16x16x32_bf16 v[0:3], v[176:179], v[246:249], v[0:3]
	v_mfma_f32_16x16x32_bf16 v[16:19], v[160:163], v[196:199], v[16:19]
	v_mfma_f32_16x16x32_bf16 v[20:23], v[176:179], v[196:199], v[20:23]
	v_mfma_f32_16x16x32_bf16 v[24:27], v[160:163], v[204:207], v[24:27]
	v_mfma_f32_16x16x32_bf16 v[28:31], v[176:179], v[204:207], v[28:31]
	s_barrier
	v_add_u32_e32 v72, 0x18000, v83
	v_add_u32_e32 v80, 0x1c000, v83
	ds_read_b128 v[48:51], v72
	ds_read_b128 v[56:59], v72 offset:1024
	ds_read_b128 v[64:67], v72 offset:2048
	ds_read_b128 v[72:75], v72 offset:3072
	ds_read_b128 v[152:155], v80
	ds_read_b128 v[160:163], v80 offset:1024
	ds_read_b128 v[168:171], v80 offset:2048
	ds_read_b128 v[176:179], v80 offset:3072
	ds_read_b128 v[192:195], v245 offset:32768
	ds_read_b128 v[196:199], v245 offset:33792
	ds_read_b128 v[200:203], v245 offset:34816
	ds_read_b128 v[204:207], v245 offset:35840
	ds_read_b128 v[220:223], v245 offset:36864
	ds_read_b128 v[224:227], v245 offset:37888
	ds_read_b128 v[228:231], v245 offset:38912
	ds_read_b128 v[246:249], v245 offset:39936
	s_add_i32 s17, s17, 0x80000
	s_mov_b32 m0, s69
	s_nop 0
	buffer_load_dwordx4 v242, s[24:27], s17 offen lds
	s_mov_b32 m0, s70
	s_nop 0
	buffer_load_dwordx4 v243, s[24:27], s17 offen lds
	s_waitcnt vmcnt(8)
	s_waitcnt lgkmcnt(0)
	s_barrier
	s_waitcnt lgkmcnt(7)
	v_mfma_f32_16x16x32_bf16 v[180:183], v[48:51], v[192:195], v[180:183]
	v_mfma_f32_16x16x32_bf16 v[164:167], v[64:67], v[192:195], v[164:167]
	s_waitcnt lgkmcnt(5)
	v_mfma_f32_16x16x32_bf16 v[148:151], v[48:51], v[200:203], v[148:151]
	v_mfma_f32_16x16x32_bf16 v[140:143], v[64:67], v[200:203], v[140:143]
	s_waitcnt lgkmcnt(3)
	v_mfma_f32_16x16x32_bf16 v[132:135], v[48:51], v[220:223], v[132:135]
	v_mfma_f32_16x16x32_bf16 v[124:127], v[64:67], v[220:223], v[124:127]
	s_waitcnt lgkmcnt(1)
	v_mfma_f32_16x16x32_bf16 v[116:119], v[48:51], v[228:231], v[116:119]
	v_mfma_f32_16x16x32_bf16 v[108:111], v[64:67], v[228:231], v[108:111]
	v_mfma_f32_16x16x32_bf16 v[180:183], v[56:59], v[196:199], v[180:183]
	v_mfma_f32_16x16x32_bf16 v[164:167], v[72:75], v[196:199], v[164:167]
	v_mfma_f32_16x16x32_bf16 v[148:151], v[56:59], v[204:207], v[148:151]
	v_mfma_f32_16x16x32_bf16 v[140:143], v[72:75], v[204:207], v[140:143]
	v_mfma_f32_16x16x32_bf16 v[132:135], v[56:59], v[224:227], v[132:135]
	v_mfma_f32_16x16x32_bf16 v[124:127], v[72:75], v[224:227], v[124:127]
	s_waitcnt lgkmcnt(0)
	v_mfma_f32_16x16x32_bf16 v[116:119], v[56:59], v[246:249], v[116:119]
	v_mfma_f32_16x16x32_bf16 v[108:111], v[72:75], v[246:249], v[108:111]
	v_mfma_f32_16x16x32_bf16 v[172:175], v[152:155], v[192:195], v[172:175]
	v_mfma_f32_16x16x32_bf16 v[156:159], v[168:171], v[192:195], v[156:159]
	v_mfma_f32_16x16x32_bf16 v[144:147], v[152:155], v[200:203], v[144:147]
	v_mfma_f32_16x16x32_bf16 v[136:139], v[168:171], v[200:203], v[136:139]
	v_mfma_f32_16x16x32_bf16 v[128:131], v[152:155], v[220:223], v[128:131]
	v_mfma_f32_16x16x32_bf16 v[120:123], v[168:171], v[220:223], v[120:123]
	v_mfma_f32_16x16x32_bf16 v[112:115], v[152:155], v[228:231], v[112:115]
	v_mfma_f32_16x16x32_bf16 v[104:107], v[168:171], v[228:231], v[104:107]
	v_mfma_f32_16x16x32_bf16 v[172:175], v[160:163], v[196:199], v[172:175]
	v_mfma_f32_16x16x32_bf16 v[156:159], v[176:179], v[196:199], v[156:159]
	v_mfma_f32_16x16x32_bf16 v[144:147], v[160:163], v[204:207], v[144:147]
	v_mfma_f32_16x16x32_bf16 v[136:139], v[176:179], v[204:207], v[136:139]
	v_mfma_f32_16x16x32_bf16 v[128:131], v[160:163], v[224:227], v[128:131]
	v_mfma_f32_16x16x32_bf16 v[120:123], v[176:179], v[224:227], v[120:123]
	v_mfma_f32_16x16x32_bf16 v[112:115], v[160:163], v[246:249], v[112:115]
	v_mfma_f32_16x16x32_bf16 v[104:107], v[176:179], v[246:249], v[104:107]
	s_barrier
	ds_read_b128 v[192:195], v245 offset:49152
	ds_read_b128 v[196:199], v245 offset:50176
	ds_read_b128 v[200:203], v245 offset:51200
	ds_read_b128 v[204:207], v245 offset:52224
	ds_read_b128 v[220:223], v245 offset:53248
	ds_read_b128 v[224:227], v245 offset:54272
	ds_read_b128 v[228:231], v245 offset:55296
	ds_read_b128 v[246:249], v245 offset:56320
	s_or_b32 s17, s16, 0x4000
	s_mov_b32 m0, s73
	s_nop 0
	buffer_load_dwordx4 v242, s[56:59], s17 offen lds
	s_add_i32 s16, s16, 0x84000
	s_mov_b32 m0, s74
	s_nop 0
	buffer_load_dwordx4 v243, s[56:59], s17 offen lds
	s_mov_b32 m0, s77
	s_nop 0
	buffer_load_dwordx4 v242, s[56:59], s16 offen lds
	s_mov_b32 m0, s78
	s_nop 0
	buffer_load_dwordx4 v243, s[56:59], s16 offen lds
	s_mov_b32 m0, s75
	s_nop 0
	buffer_load_dwordx4 v242, s[24:27], s7 offen lds
	s_mov_b32 m0, s76
	s_nop 0
	buffer_load_dwordx4 v243, s[24:27], s7 offen lds
	s_waitcnt vmcnt(8)
	s_waitcnt lgkmcnt(0)
	s_barrier
	s_waitcnt lgkmcnt(7)
	v_mfma_f32_16x16x32_bf16 v[76:79], v[48:51], v[192:195], v[76:79]
	v_mfma_f32_16x16x32_bf16 v[68:71], v[64:67], v[192:195], v[68:71]
	s_waitcnt lgkmcnt(5)
	v_mfma_f32_16x16x32_bf16 v[60:63], v[48:51], v[200:203], v[60:63]
	v_mfma_f32_16x16x32_bf16 v[52:55], v[64:67], v[200:203], v[52:55]
	s_waitcnt lgkmcnt(3)
	v_mfma_f32_16x16x32_bf16 v[44:47], v[48:51], v[220:223], v[44:47]
	v_mfma_f32_16x16x32_bf16 v[36:39], v[64:67], v[220:223], v[36:39]
	s_waitcnt lgkmcnt(1)
	v_mfma_f32_16x16x32_bf16 v[12:15], v[48:51], v[228:231], v[12:15]
	v_mfma_f32_16x16x32_bf16 v[4:7], v[64:67], v[228:231], v[4:7]
	v_mfma_f32_16x16x32_bf16 v[76:79], v[56:59], v[196:199], v[76:79]
	v_mfma_f32_16x16x32_bf16 v[68:71], v[72:75], v[196:199], v[68:71]
	v_mfma_f32_16x16x32_bf16 v[60:63], v[56:59], v[204:207], v[60:63]
	v_mfma_f32_16x16x32_bf16 v[52:55], v[72:75], v[204:207], v[52:55]
	v_mfma_f32_16x16x32_bf16 v[44:47], v[56:59], v[224:227], v[44:47]
	v_mfma_f32_16x16x32_bf16 v[36:39], v[72:75], v[224:227], v[36:39]
	s_waitcnt lgkmcnt(0)
	v_mfma_f32_16x16x32_bf16 v[12:15], v[56:59], v[246:249], v[12:15]
	v_mfma_f32_16x16x32_bf16 v[4:7], v[72:75], v[246:249], v[4:7]
	v_mfma_f32_16x16x32_bf16 v[16:19], v[152:155], v[192:195], v[16:19]
	v_mfma_f32_16x16x32_bf16 v[72:75], v[160:163], v[196:199], v[16:19]
	v_mfma_f32_16x16x32_bf16 v[16:19], v[168:171], v[192:195], v[20:23]
	v_mfma_f32_16x16x32_bf16 v[64:67], v[176:179], v[196:199], v[16:19]
	v_mfma_f32_16x16x32_bf16 v[16:19], v[152:155], v[200:203], v[24:27]
	v_mfma_f32_16x16x32_bf16 v[56:59], v[160:163], v[204:207], v[16:19]
	v_mfma_f32_16x16x32_bf16 v[16:19], v[168:171], v[200:203], v[28:31]
	v_mfma_f32_16x16x32_bf16 v[48:51], v[176:179], v[204:207], v[16:19]
	v_mfma_f32_16x16x32_bf16 v[16:19], v[152:155], v[220:223], v[40:43]
	v_mfma_f32_16x16x32_bf16 v[40:43], v[160:163], v[224:227], v[16:19]
	v_mfma_f32_16x16x32_bf16 v[16:19], v[168:171], v[220:223], v[32:35]
	v_mfma_f32_16x16x32_bf16 v[8:11], v[152:155], v[228:231], v[8:11]
	v_mfma_f32_16x16x32_bf16 v[0:3], v[168:171], v[228:231], v[0:3]
	v_mfma_f32_16x16x32_bf16 v[32:35], v[176:179], v[224:227], v[16:19]
	v_mfma_f32_16x16x32_bf16 v[8:11], v[160:163], v[246:249], v[8:11]
	v_mfma_f32_16x16x32_bf16 v[0:3], v[176:179], v[246:249], v[0:3]
	s_barrier
	s_add_i32 s6, s6, 2
	s_add_i32 s4, s4, 0x8000
	s_add_i32 s5, s5, 0x8000
	s_cmp_gt_u32 s6, 29
	s_cbranch_scc0 .LBB0_143

.LBB0_594:
	v_add_u32_e32 v80, 0x10000, v226
	ds_read_b128 v[152:155], v80
	ds_read_b128 v[156:159], v80 offset:1024
	ds_read_b128 v[160:163], v80 offset:2048
	ds_read_b128 v[164:167], v80 offset:3072
	v_add_u32_e32 v80, 0x14000, v226
	ds_read_b128 v[168:171], v80
	ds_read_b128 v[172:175], v80 offset:1024
	ds_read_b128 v[176:179], v80 offset:2048
	ds_read_b128 v[180:183], v80 offset:3072
	s_add_i32 s97, s96, s39
	s_add_i32 s94, s97, 0x8000
	s_add_i32 s95, s93, s39
	s_cmp_eq_u32 s39, 0x78000
	s_cselect_b32 s36, vcc_lo, s94
	s_cselect_b32 s95, vcc_hi, s95
	s_or_b32 s94, s36, 0x4000
	ds_read_b128 v[184:187], v227
	ds_read_b128 v[188:191], v227 offset:1024
	ds_read_b128 v[192:195], v227 offset:2048
	ds_read_b128 v[196:199], v227 offset:3072
	ds_read_b128 v[200:203], v227 offset:4096
	ds_read_b128 v[204:207], v227 offset:5120
	ds_read_b128 v[228:231], v227 offset:6144
	ds_read_b128 v[240:243], v227 offset:7168
	s_add_i32 s97, s97, 0x84000
	s_mov_b32 m0, s85
	s_nop 0
	buffer_load_dwordx4 v224, s[60:63], s97 offen lds
	s_mov_b32 m0, s86
	s_nop 0
	buffer_load_dwordx4 v225, s[60:63], s97 offen lds
	s_waitcnt vmcnt(8)
	s_waitcnt lgkmcnt(0)
	s_barrier
	s_waitcnt lgkmcnt(7)
	v_mfma_f32_16x16x32_bf16 v[148:151], v[152:155], v[184:187], v[148:151]
	v_mfma_f32_16x16x32_bf16 v[144:147], v[160:163], v[184:187], v[144:147]
	s_waitcnt lgkmcnt(5)
	v_mfma_f32_16x16x32_bf16 v[132:135], v[152:155], v[192:195], v[132:135]
	v_mfma_f32_16x16x32_bf16 v[128:131], v[160:163], v[192:195], v[128:131]
	s_waitcnt lgkmcnt(3)
	v_mfma_f32_16x16x32_bf16 v[116:119], v[152:155], v[200:203], v[116:119]
	v_mfma_f32_16x16x32_bf16 v[112:115], v[160:163], v[200:203], v[112:115]
	s_waitcnt lgkmcnt(1)
	v_mfma_f32_16x16x32_bf16 v[76:79], v[152:155], v[228:231], v[76:79]
	v_mfma_f32_16x16x32_bf16 v[72:75], v[160:163], v[228:231], v[72:75]
	v_mfma_f32_16x16x32_bf16 v[148:151], v[156:159], v[188:191], v[148:151]
	v_mfma_f32_16x16x32_bf16 v[144:147], v[164:167], v[188:191], v[144:147]
	v_mfma_f32_16x16x32_bf16 v[132:135], v[156:159], v[196:199], v[132:135]
	v_mfma_f32_16x16x32_bf16 v[128:131], v[164:167], v[196:199], v[128:131]
	v_mfma_f32_16x16x32_bf16 v[116:119], v[156:159], v[204:207], v[116:119]
	v_mfma_f32_16x16x32_bf16 v[112:115], v[164:167], v[204:207], v[112:115]
	s_waitcnt lgkmcnt(0)
	v_mfma_f32_16x16x32_bf16 v[76:79], v[156:159], v[240:243], v[76:79]
	v_mfma_f32_16x16x32_bf16 v[72:75], v[164:167], v[240:243], v[72:75]
	v_mfma_f32_16x16x32_bf16 v[140:143], v[168:171], v[184:187], v[140:143]
	v_mfma_f32_16x16x32_bf16 v[136:139], v[176:179], v[184:187], v[136:139]
	v_mfma_f32_16x16x32_bf16 v[124:127], v[168:171], v[192:195], v[124:127]
	v_mfma_f32_16x16x32_bf16 v[120:123], v[176:179], v[192:195], v[120:123]
	v_mfma_f32_16x16x32_bf16 v[108:111], v[168:171], v[200:203], v[108:111]
	v_mfma_f32_16x16x32_bf16 v[104:107], v[176:179], v[200:203], v[104:107]
	v_mfma_f32_16x16x32_bf16 v[68:71], v[168:171], v[228:231], v[68:71]
	v_mfma_f32_16x16x32_bf16 v[64:67], v[176:179], v[228:231], v[64:67]
	v_mfma_f32_16x16x32_bf16 v[140:143], v[172:175], v[188:191], v[140:143]
	v_mfma_f32_16x16x32_bf16 v[136:139], v[180:183], v[188:191], v[136:139]
	v_mfma_f32_16x16x32_bf16 v[124:127], v[172:175], v[196:199], v[124:127]
	v_mfma_f32_16x16x32_bf16 v[120:123], v[180:183], v[196:199], v[120:123]
	v_mfma_f32_16x16x32_bf16 v[108:111], v[172:175], v[204:207], v[108:111]
	v_mfma_f32_16x16x32_bf16 v[104:107], v[180:183], v[204:207], v[104:107]
	v_mfma_f32_16x16x32_bf16 v[68:71], v[172:175], v[240:243], v[68:71]
	v_mfma_f32_16x16x32_bf16 v[64:67], v[180:183], v[240:243], v[64:67]
	s_barrier
	ds_read_b128 v[184:187], v227 offset:16384
	ds_read_b128 v[188:191], v227 offset:17408
	ds_read_b128 v[192:195], v227 offset:18432
	ds_read_b128 v[196:199], v227 offset:19456
	ds_read_b128 v[200:203], v227 offset:20480
	ds_read_b128 v[204:207], v227 offset:21504
	ds_read_b128 v[228:231], v227 offset:22528
	ds_read_b128 v[240:243], v227 offset:23552
	s_mov_b32 m0, s34
	s_nop 0
	buffer_load_dwordx4 v224, s[48:51], s95 offen lds
	s_add_i32 s97, s95, 0x80000
	s_mov_b32 m0, s55
	s_nop 0
	buffer_load_dwordx4 v225, s[48:51], s95 offen lds
	s_mov_b32 m0, s72
	s_nop 0
	buffer_load_dwordx4 v224, s[48:51], s97 offen lds
	s_mov_b32 m0, s73
	s_nop 0
	buffer_load_dwordx4 v225, s[48:51], s97 offen lds
	s_mov_b32 m0, s31
	s_nop 0
	buffer_load_dwordx4 v224, s[60:63], s36 offen lds
	s_mov_b32 m0, s74
	s_nop 0
	buffer_load_dwordx4 v225, s[60:63], s36 offen lds
	s_waitcnt vmcnt(8)
	s_waitcnt lgkmcnt(0)
	s_barrier
	s_waitcnt lgkmcnt(7)
	v_mfma_f32_16x16x32_bf16 v[60:63], v[152:155], v[184:187], v[60:63]
	v_mfma_f32_16x16x32_bf16 v[56:59], v[160:163], v[184:187], v[56:59]
	s_waitcnt lgkmcnt(5)
	v_mfma_f32_16x16x32_bf16 v[44:47], v[152:155], v[192:195], v[44:47]
	v_mfma_f32_16x16x32_bf16 v[40:43], v[160:163], v[192:195], v[40:43]
	s_waitcnt lgkmcnt(3)
	v_mfma_f32_16x16x32_bf16 v[28:31], v[152:155], v[200:203], v[28:31]
	v_mfma_f32_16x16x32_bf16 v[24:27], v[160:163], v[200:203], v[24:27]
	s_waitcnt lgkmcnt(1)
	v_mfma_f32_16x16x32_bf16 v[12:15], v[152:155], v[228:231], v[12:15]
	v_mfma_f32_16x16x32_bf16 v[8:11], v[160:163], v[228:231], v[8:11]
	v_mfma_f32_16x16x32_bf16 v[60:63], v[156:159], v[188:191], v[60:63]
	v_mfma_f32_16x16x32_bf16 v[56:59], v[164:167], v[188:191], v[56:59]
	v_mfma_f32_16x16x32_bf16 v[44:47], v[156:159], v[196:199], v[44:47]
	v_mfma_f32_16x16x32_bf16 v[40:43], v[164:167], v[196:199], v[40:43]
	v_mfma_f32_16x16x32_bf16 v[28:31], v[156:159], v[204:207], v[28:31]
	v_mfma_f32_16x16x32_bf16 v[24:27], v[164:167], v[204:207], v[24:27]
	s_waitcnt lgkmcnt(0)
	v_mfma_f32_16x16x32_bf16 v[12:15], v[156:159], v[240:243], v[12:15]
	v_mfma_f32_16x16x32_bf16 v[8:11], v[164:167], v[240:243], v[8:11]
	v_mfma_f32_16x16x32_bf16 v[52:55], v[168:171], v[184:187], v[52:55]
	v_mfma_f32_16x16x32_bf16 v[48:51], v[176:179], v[184:187], v[48:51]
	v_mfma_f32_16x16x32_bf16 v[36:39], v[168:171], v[192:195], v[36:39]
	v_mfma_f32_16x16x32_bf16 v[32:35], v[176:179], v[192:195], v[32:35]
	v_mfma_f32_16x16x32_bf16 v[20:23], v[168:171], v[200:203], v[20:23]
	v_mfma_f32_16x16x32_bf16 v[16:19], v[176:179], v[200:203], v[16:19]
	v_mfma_f32_16x16x32_bf16 v[4:7], v[168:171], v[228:231], v[4:7]
	v_mfma_f32_16x16x32_bf16 v[0:3], v[176:179], v[228:231], v[0:3]
	v_mfma_f32_16x16x32_bf16 v[52:55], v[172:175], v[188:191], v[52:55]
	v_mfma_f32_16x16x32_bf16 v[48:51], v[180:183], v[188:191], v[48:51]
	v_mfma_f32_16x16x32_bf16 v[36:39], v[172:175], v[196:199], v[36:39]
	v_mfma_f32_16x16x32_bf16 v[32:35], v[180:183], v[196:199], v[32:35]
	v_mfma_f32_16x16x32_bf16 v[20:23], v[172:175], v[204:207], v[20:23]
	v_mfma_f32_16x16x32_bf16 v[16:19], v[180:183], v[204:207], v[16:19]
	v_mfma_f32_16x16x32_bf16 v[4:7], v[172:175], v[240:243], v[4:7]
	v_mfma_f32_16x16x32_bf16 v[0:3], v[180:183], v[240:243], v[0:3]
	s_barrier
	v_add_u32_e32 v80, 0x18000, v226
	ds_read_b128 v[152:155], v80
	ds_read_b128 v[156:159], v80 offset:1024
	ds_read_b128 v[160:163], v80 offset:2048
	ds_read_b128 v[164:167], v80 offset:3072
	v_add_u32_e32 v80, 0x1c000, v226
	ds_read_b128 v[168:171], v80
	ds_read_b128 v[172:175], v80 offset:1024
	ds_read_b128 v[176:179], v80 offset:2048
	ds_read_b128 v[180:183], v80 offset:3072
	ds_read_b128 v[184:187], v227 offset:32768
	ds_read_b128 v[188:191], v227 offset:33792
	ds_read_b128 v[192:195], v227 offset:34816
	ds_read_b128 v[196:199], v227 offset:35840
	ds_read_b128 v[200:203], v227 offset:36864
	ds_read_b128 v[204:207], v227 offset:37888
	ds_read_b128 v[228:231], v227 offset:38912
	ds_read_b128 v[240:243], v227 offset:39936
	s_add_i32 s36, s36, 0x80000
	s_mov_b32 m0, s75
	s_nop 0
	buffer_load_dwordx4 v224, s[60:63], s36 offen lds
	s_mov_b32 m0, s76
	s_nop 0
	buffer_load_dwordx4 v225, s[60:63], s36 offen lds
	s_waitcnt vmcnt(8)
	s_waitcnt lgkmcnt(0)
	s_barrier
	s_waitcnt lgkmcnt(7)
	v_mfma_f32_16x16x32_bf16 v[148:151], v[152:155], v[184:187], v[148:151]
	v_mfma_f32_16x16x32_bf16 v[144:147], v[160:163], v[184:187], v[144:147]
	s_waitcnt lgkmcnt(5)
	v_mfma_f32_16x16x32_bf16 v[132:135], v[152:155], v[192:195], v[132:135]
	v_mfma_f32_16x16x32_bf16 v[128:131], v[160:163], v[192:195], v[128:131]
	s_waitcnt lgkmcnt(3)
	v_mfma_f32_16x16x32_bf16 v[116:119], v[152:155], v[200:203], v[116:119]
	v_mfma_f32_16x16x32_bf16 v[112:115], v[160:163], v[200:203], v[112:115]
	s_waitcnt lgkmcnt(1)
	v_mfma_f32_16x16x32_bf16 v[76:79], v[152:155], v[228:231], v[76:79]
	v_mfma_f32_16x16x32_bf16 v[72:75], v[160:163], v[228:231], v[72:75]
	v_mfma_f32_16x16x32_bf16 v[148:151], v[156:159], v[188:191], v[148:151]
	v_mfma_f32_16x16x32_bf16 v[144:147], v[164:167], v[188:191], v[144:147]
	v_mfma_f32_16x16x32_bf16 v[132:135], v[156:159], v[196:199], v[132:135]
	v_mfma_f32_16x16x32_bf16 v[128:131], v[164:167], v[196:199], v[128:131]
	v_mfma_f32_16x16x32_bf16 v[116:119], v[156:159], v[204:207], v[116:119]
	v_mfma_f32_16x16x32_bf16 v[112:115], v[164:167], v[204:207], v[112:115]
	s_waitcnt lgkmcnt(0)
	v_mfma_f32_16x16x32_bf16 v[76:79], v[156:159], v[240:243], v[76:79]
	v_mfma_f32_16x16x32_bf16 v[72:75], v[164:167], v[240:243], v[72:75]
	v_mfma_f32_16x16x32_bf16 v[140:143], v[168:171], v[184:187], v[140:143]
	v_mfma_f32_16x16x32_bf16 v[136:139], v[176:179], v[184:187], v[136:139]
	v_mfma_f32_16x16x32_bf16 v[124:127], v[168:171], v[192:195], v[124:127]
	v_mfma_f32_16x16x32_bf16 v[120:123], v[176:179], v[192:195], v[120:123]
	v_mfma_f32_16x16x32_bf16 v[108:111], v[168:171], v[200:203], v[108:111]
	v_mfma_f32_16x16x32_bf16 v[104:107], v[176:179], v[200:203], v[104:107]
	v_mfma_f32_16x16x32_bf16 v[68:71], v[168:171], v[228:231], v[68:71]
	v_mfma_f32_16x16x32_bf16 v[64:67], v[176:179], v[228:231], v[64:67]
	v_mfma_f32_16x16x32_bf16 v[140:143], v[172:175], v[188:191], v[140:143]
	v_mfma_f32_16x16x32_bf16 v[136:139], v[180:183], v[188:191], v[136:139]
	v_mfma_f32_16x16x32_bf16 v[124:127], v[172:175], v[196:199], v[124:127]
	v_mfma_f32_16x16x32_bf16 v[120:123], v[180:183], v[196:199], v[120:123]
	v_mfma_f32_16x16x32_bf16 v[108:111], v[172:175], v[204:207], v[108:111]
	v_mfma_f32_16x16x32_bf16 v[104:107], v[180:183], v[204:207], v[104:107]
	v_mfma_f32_16x16x32_bf16 v[68:71], v[172:175], v[240:243], v[68:71]
	v_mfma_f32_16x16x32_bf16 v[64:67], v[180:183], v[240:243], v[64:67]
	s_barrier
	ds_read_b128 v[184:187], v227 offset:49152
	ds_read_b128 v[188:191], v227 offset:50176
	ds_read_b128 v[192:195], v227 offset:51200
	ds_read_b128 v[196:199], v227 offset:52224
	ds_read_b128 v[200:203], v227 offset:53248
	ds_read_b128 v[204:207], v227 offset:54272
	ds_read_b128 v[228:231], v227 offset:55296
	ds_read_b128 v[240:243], v227 offset:56320
	s_or_b32 s36, s95, 0x4000
	s_mov_b32 m0, s77
	s_nop 0
	buffer_load_dwordx4 v224, s[48:51], s36 offen lds
	s_mov_b32 m0, s78
	s_nop 0
	buffer_load_dwordx4 v225, s[48:51], s36 offen lds
	s_add_i32 s36, s95, 0x84000
	s_mov_b32 m0, s83
	s_nop 0
	buffer_load_dwordx4 v224, s[48:51], s36 offen lds
	s_mov_b32 m0, s84
	s_nop 0
	buffer_load_dwordx4 v225, s[48:51], s36 offen lds
	s_mov_b32 m0, s79
	s_nop 0
	buffer_load_dwordx4 v224, s[60:63], s94 offen lds
	s_mov_b32 m0, s82
	s_nop 0
	buffer_load_dwordx4 v225, s[60:63], s94 offen lds
	s_waitcnt vmcnt(8)
	s_waitcnt lgkmcnt(0)
	s_barrier
	s_waitcnt lgkmcnt(7)
	v_mfma_f32_16x16x32_bf16 v[60:63], v[152:155], v[184:187], v[60:63]
	v_mfma_f32_16x16x32_bf16 v[56:59], v[160:163], v[184:187], v[56:59]
	s_waitcnt lgkmcnt(5)
	v_mfma_f32_16x16x32_bf16 v[44:47], v[152:155], v[192:195], v[44:47]
	v_mfma_f32_16x16x32_bf16 v[40:43], v[160:163], v[192:195], v[40:43]
	s_waitcnt lgkmcnt(3)
	v_mfma_f32_16x16x32_bf16 v[28:31], v[152:155], v[200:203], v[28:31]
	v_mfma_f32_16x16x32_bf16 v[24:27], v[160:163], v[200:203], v[24:27]
	s_waitcnt lgkmcnt(1)
	v_mfma_f32_16x16x32_bf16 v[12:15], v[152:155], v[228:231], v[12:15]
	v_mfma_f32_16x16x32_bf16 v[8:11], v[160:163], v[228:231], v[8:11]
	v_mfma_f32_16x16x32_bf16 v[60:63], v[156:159], v[188:191], v[60:63]
	v_mfma_f32_16x16x32_bf16 v[56:59], v[164:167], v[188:191], v[56:59]
	v_mfma_f32_16x16x32_bf16 v[44:47], v[156:159], v[196:199], v[44:47]
	v_mfma_f32_16x16x32_bf16 v[40:43], v[164:167], v[196:199], v[40:43]
	v_mfma_f32_16x16x32_bf16 v[28:31], v[156:159], v[204:207], v[28:31]
	v_mfma_f32_16x16x32_bf16 v[24:27], v[164:167], v[204:207], v[24:27]
	s_waitcnt lgkmcnt(0)
	v_mfma_f32_16x16x32_bf16 v[12:15], v[156:159], v[240:243], v[12:15]
	v_mfma_f32_16x16x32_bf16 v[8:11], v[164:167], v[240:243], v[8:11]
	v_mfma_f32_16x16x32_bf16 v[52:55], v[168:171], v[184:187], v[52:55]
	v_mfma_f32_16x16x32_bf16 v[48:51], v[176:179], v[184:187], v[48:51]
	v_mfma_f32_16x16x32_bf16 v[36:39], v[168:171], v[192:195], v[36:39]
	v_mfma_f32_16x16x32_bf16 v[32:35], v[176:179], v[192:195], v[32:35]
	v_mfma_f32_16x16x32_bf16 v[20:23], v[168:171], v[200:203], v[20:23]
	v_mfma_f32_16x16x32_bf16 v[16:19], v[176:179], v[200:203], v[16:19]
	v_mfma_f32_16x16x32_bf16 v[4:7], v[168:171], v[228:231], v[4:7]
	v_mfma_f32_16x16x32_bf16 v[0:3], v[176:179], v[228:231], v[0:3]
	v_mfma_f32_16x16x32_bf16 v[52:55], v[172:175], v[188:191], v[52:55]
	v_mfma_f32_16x16x32_bf16 v[48:51], v[180:183], v[188:191], v[48:51]
	v_mfma_f32_16x16x32_bf16 v[36:39], v[172:175], v[196:199], v[36:39]
	v_mfma_f32_16x16x32_bf16 v[32:35], v[180:183], v[196:199], v[32:35]
	v_mfma_f32_16x16x32_bf16 v[20:23], v[172:175], v[204:207], v[20:23]
	v_mfma_f32_16x16x32_bf16 v[16:19], v[180:183], v[204:207], v[16:19]
	v_mfma_f32_16x16x32_bf16 v[4:7], v[172:175], v[240:243], v[4:7]
	v_mfma_f32_16x16x32_bf16 v[0:3], v[180:183], v[240:243], v[0:3]
	s_barrier
	s_add_i32 s38, s38, 2
	s_add_i32 s39, s39, 0x8000
	s_cmp_gt_u32 s38, 29
	s_cbranch_scc1 .LBB0_597

.Lnb_p4:
	s_add_i32 s11, s8, 0xfff84000
	s_cmp_eq_u32 s10, 28
	s_cselect_b32 s13, s6, s11
	s_cselect_b32 s12, s7, s9
	s_or_b32 s11, s13, 0x4000
	s_mov_b32 m0, s89
	s_nop 0
	buffer_load_dwordx4 v220, s[64:67], s8 offen lds
	s_mov_b32 m0, s91
	s_nop 0
	buffer_load_dwordx4 v221, s[64:67], s8 offen lds
	s_waitcnt vmcnt(24)
	s_waitcnt lgkmcnt(0)
	s_barrier
	s_waitcnt lgkmcnt(7)
	v_mfma_f32_16x16x32_bf16 v[164:167], v[128:131], v[184:187], 0
	v_mfma_f32_16x16x32_bf16 v[160:163], v[152:155], v[184:187], 0
	s_waitcnt lgkmcnt(5)
	v_mfma_f32_16x16x32_bf16 v[136:139], v[128:131], v[192:195], 0
	v_mfma_f32_16x16x32_bf16 v[132:135], v[152:155], v[192:195], 0
	s_waitcnt lgkmcnt(3)
	v_mfma_f32_16x16x32_bf16 v[116:119], v[128:131], v[200:203], 0
	v_mfma_f32_16x16x32_bf16 v[112:115], v[152:155], v[200:203], 0
	s_waitcnt lgkmcnt(1)
	v_mfma_f32_16x16x32_bf16 v[76:79], v[128:131], v[224:227], 0
	v_mfma_f32_16x16x32_bf16 v[72:75], v[152:155], v[224:227], 0
	v_mfma_f32_16x16x32_bf16 v[164:167], v[140:143], v[188:191], v[164:167]
	v_mfma_f32_16x16x32_bf16 v[160:163], v[156:159], v[188:191], v[160:163]
	v_mfma_f32_16x16x32_bf16 v[136:139], v[140:143], v[196:199], v[136:139]
	v_mfma_f32_16x16x32_bf16 v[132:135], v[156:159], v[196:199], v[132:135]
	v_mfma_f32_16x16x32_bf16 v[116:119], v[140:143], v[204:207], v[116:119]
	v_mfma_f32_16x16x32_bf16 v[112:115], v[156:159], v[204:207], v[112:115]
	s_waitcnt lgkmcnt(0)
	v_mfma_f32_16x16x32_bf16 v[76:79], v[140:143], v[228:231], v[76:79]
	v_mfma_f32_16x16x32_bf16 v[72:75], v[156:159], v[228:231], v[72:75]
	v_mfma_f32_16x16x32_bf16 v[148:151], v[168:171], v[184:187], 0
	v_mfma_f32_16x16x32_bf16 v[144:147], v[176:179], v[184:187], 0
	v_mfma_f32_16x16x32_bf16 v[124:127], v[168:171], v[192:195], 0
	v_mfma_f32_16x16x32_bf16 v[120:123], v[176:179], v[192:195], 0
	v_mfma_f32_16x16x32_bf16 v[108:111], v[168:171], v[200:203], 0
	v_mfma_f32_16x16x32_bf16 v[104:107], v[176:179], v[200:203], 0
	v_mfma_f32_16x16x32_bf16 v[68:71], v[168:171], v[224:227], 0
	v_mfma_f32_16x16x32_bf16 v[64:67], v[176:179], v[224:227], 0
	v_mfma_f32_16x16x32_bf16 v[148:151], v[172:175], v[188:191], v[148:151]
	v_mfma_f32_16x16x32_bf16 v[144:147], v[180:183], v[188:191], v[144:147]
	v_mfma_f32_16x16x32_bf16 v[124:127], v[172:175], v[196:199], v[124:127]
	v_mfma_f32_16x16x32_bf16 v[120:123], v[180:183], v[196:199], v[120:123]
	v_mfma_f32_16x16x32_bf16 v[108:111], v[172:175], v[204:207], v[108:111]
	v_mfma_f32_16x16x32_bf16 v[104:107], v[180:183], v[204:207], v[104:107]
	v_mfma_f32_16x16x32_bf16 v[68:71], v[172:175], v[228:231], v[68:71]
	v_mfma_f32_16x16x32_bf16 v[64:67], v[180:183], v[228:231], v[64:67]
	s_barrier
	ds_read_b128 v[184:187], v223 offset:16384
	ds_read_b128 v[188:191], v223 offset:17408
	ds_read_b128 v[192:195], v223 offset:18432
	ds_read_b128 v[196:199], v223 offset:19456
	ds_read_b128 v[200:203], v223 offset:20480
	ds_read_b128 v[204:207], v223 offset:21504
	ds_read_b128 v[224:227], v223 offset:22528
	ds_read_b128 v[228:231], v223 offset:23552
	s_mov_b32 m0, s55
	s_nop 0
	buffer_load_dwordx4 v220, s[48:51], s12 offen lds
	s_add_i32 s14, s12, 0x80000
	s_mov_b32 m0, s76
	s_nop 0
	buffer_load_dwordx4 v221, s[48:51], s12 offen lds
	s_mov_b32 m0, s77
	s_nop 0
	buffer_load_dwordx4 v220, s[48:51], s14 offen lds
	s_mov_b32 m0, s78
	s_nop 0
	buffer_load_dwordx4 v221, s[48:51], s14 offen lds
	s_mov_b32 m0, s31
	s_nop 0
	buffer_load_dwordx4 v220, s[64:67], s13 offen lds
	s_mov_b32 m0, s79
	s_nop 0
	buffer_load_dwordx4 v221, s[64:67], s13 offen lds
	s_waitcnt vmcnt(24)
	s_waitcnt lgkmcnt(0)
	s_barrier
	s_waitcnt lgkmcnt(7)
	v_mfma_f32_16x16x32_bf16 v[60:63], v[128:131], v[184:187], 0
	v_mfma_f32_16x16x32_bf16 v[56:59], v[152:155], v[184:187], 0
	s_waitcnt lgkmcnt(5)
	v_mfma_f32_16x16x32_bf16 v[44:47], v[128:131], v[192:195], 0
	v_mfma_f32_16x16x32_bf16 v[40:43], v[152:155], v[192:195], 0
	s_waitcnt lgkmcnt(3)
	v_mfma_f32_16x16x32_bf16 v[28:31], v[128:131], v[200:203], 0
	v_mfma_f32_16x16x32_bf16 v[24:27], v[152:155], v[200:203], 0
	s_waitcnt lgkmcnt(1)
	v_mfma_f32_16x16x32_bf16 v[12:15], v[128:131], v[224:227], 0
	v_mfma_f32_16x16x32_bf16 v[8:11], v[152:155], v[224:227], 0
	v_mfma_f32_16x16x32_bf16 v[60:63], v[140:143], v[188:191], v[60:63]
	v_mfma_f32_16x16x32_bf16 v[56:59], v[156:159], v[188:191], v[56:59]
	v_mfma_f32_16x16x32_bf16 v[44:47], v[140:143], v[196:199], v[44:47]
	v_mfma_f32_16x16x32_bf16 v[40:43], v[156:159], v[196:199], v[40:43]
	v_mfma_f32_16x16x32_bf16 v[28:31], v[140:143], v[204:207], v[28:31]
	v_mfma_f32_16x16x32_bf16 v[24:27], v[156:159], v[204:207], v[24:27]
	s_waitcnt lgkmcnt(0)
	v_mfma_f32_16x16x32_bf16 v[12:15], v[140:143], v[228:231], v[12:15]
	v_mfma_f32_16x16x32_bf16 v[8:11], v[156:159], v[228:231], v[8:11]
	v_mfma_f32_16x16x32_bf16 v[52:55], v[168:171], v[184:187], 0
	v_mfma_f32_16x16x32_bf16 v[48:51], v[176:179], v[184:187], 0
	v_mfma_f32_16x16x32_bf16 v[36:39], v[168:171], v[192:195], 0
	v_mfma_f32_16x16x32_bf16 v[32:35], v[176:179], v[192:195], 0
	v_mfma_f32_16x16x32_bf16 v[20:23], v[168:171], v[200:203], 0
	v_mfma_f32_16x16x32_bf16 v[16:19], v[176:179], v[200:203], 0
	v_mfma_f32_16x16x32_bf16 v[4:7], v[168:171], v[224:227], 0
	v_mfma_f32_16x16x32_bf16 v[0:3], v[176:179], v[224:227], 0
	v_mfma_f32_16x16x32_bf16 v[52:55], v[172:175], v[188:191], v[52:55]
	v_mfma_f32_16x16x32_bf16 v[48:51], v[180:183], v[188:191], v[48:51]
	v_mfma_f32_16x16x32_bf16 v[36:39], v[172:175], v[196:199], v[36:39]
	v_mfma_f32_16x16x32_bf16 v[32:35], v[180:183], v[196:199], v[32:35]
	v_mfma_f32_16x16x32_bf16 v[20:23], v[172:175], v[204:207], v[20:23]
	v_mfma_f32_16x16x32_bf16 v[16:19], v[180:183], v[204:207], v[16:19]
	v_mfma_f32_16x16x32_bf16 v[4:7], v[172:175], v[228:231], v[4:7]
	v_mfma_f32_16x16x32_bf16 v[0:3], v[180:183], v[228:231], v[0:3]
	s_barrier
	v_add_u32_e32 v156, 0x18000, v222
	v_add_u32_e32 v180, 0x1c000, v222
	ds_read_b128 v[128:131], v156
	ds_read_b128 v[140:143], v156 offset:1024
	ds_read_b128 v[152:155], v156 offset:2048
	ds_read_b128 v[156:159], v156 offset:3072
	ds_read_b128 v[168:171], v180
	ds_read_b128 v[172:175], v180 offset:1024
	ds_read_b128 v[176:179], v180 offset:2048
	ds_read_b128 v[180:183], v180 offset:3072
	ds_read_b128 v[184:187], v223 offset:32768
	ds_read_b128 v[188:191], v223 offset:33792
	ds_read_b128 v[192:195], v223 offset:34816
	ds_read_b128 v[196:199], v223 offset:35840
	ds_read_b128 v[200:203], v223 offset:36864
	ds_read_b128 v[204:207], v223 offset:37888
	ds_read_b128 v[224:227], v223 offset:38912
	ds_read_b128 v[228:231], v223 offset:39936
	s_add_i32 s13, s13, 0x80000
	s_mov_b32 m0, s82
	s_nop 0
	buffer_load_dwordx4 v220, s[64:67], s13 offen lds
	s_mov_b32 m0, s83
	s_nop 0
	buffer_load_dwordx4 v221, s[64:67], s13 offen lds
	s_waitcnt vmcnt(8)
	s_waitcnt lgkmcnt(0)
	s_barrier
	s_waitcnt lgkmcnt(7)
	v_mfma_f32_16x16x32_bf16 v[164:167], v[128:131], v[184:187], v[164:167]
	v_mfma_f32_16x16x32_bf16 v[160:163], v[152:155], v[184:187], v[160:163]
	s_waitcnt lgkmcnt(5)
	v_mfma_f32_16x16x32_bf16 v[136:139], v[128:131], v[192:195], v[136:139]
	v_mfma_f32_16x16x32_bf16 v[132:135], v[152:155], v[192:195], v[132:135]
	s_waitcnt lgkmcnt(3)
	v_mfma_f32_16x16x32_bf16 v[116:119], v[128:131], v[200:203], v[116:119]
	v_mfma_f32_16x16x32_bf16 v[112:115], v[152:155], v[200:203], v[112:115]
	s_waitcnt lgkmcnt(1)
	v_mfma_f32_16x16x32_bf16 v[76:79], v[128:131], v[224:227], v[76:79]
	v_mfma_f32_16x16x32_bf16 v[72:75], v[152:155], v[224:227], v[72:75]
	v_mfma_f32_16x16x32_bf16 v[164:167], v[140:143], v[188:191], v[164:167]
	v_mfma_f32_16x16x32_bf16 v[160:163], v[156:159], v[188:191], v[160:163]
	v_mfma_f32_16x16x32_bf16 v[136:139], v[140:143], v[196:199], v[136:139]
	v_mfma_f32_16x16x32_bf16 v[132:135], v[156:159], v[196:199], v[132:135]
	v_mfma_f32_16x16x32_bf16 v[116:119], v[140:143], v[204:207], v[116:119]
	v_mfma_f32_16x16x32_bf16 v[112:115], v[156:159], v[204:207], v[112:115]
	s_waitcnt lgkmcnt(0)
	v_mfma_f32_16x16x32_bf16 v[76:79], v[140:143], v[228:231], v[76:79]
	v_mfma_f32_16x16x32_bf16 v[72:75], v[156:159], v[228:231], v[72:75]
	v_mfma_f32_16x16x32_bf16 v[148:151], v[168:171], v[184:187], v[148:151]
	v_mfma_f32_16x16x32_bf16 v[144:147], v[176:179], v[184:187], v[144:147]
	v_mfma_f32_16x16x32_bf16 v[124:127], v[168:171], v[192:195], v[124:127]
	v_mfma_f32_16x16x32_bf16 v[120:123], v[176:179], v[192:195], v[120:123]
	v_mfma_f32_16x16x32_bf16 v[108:111], v[168:171], v[200:203], v[108:111]
	v_mfma_f32_16x16x32_bf16 v[104:107], v[176:179], v[200:203], v[104:107]
	v_mfma_f32_16x16x32_bf16 v[68:71], v[168:171], v[224:227], v[68:71]
	v_mfma_f32_16x16x32_bf16 v[64:67], v[176:179], v[224:227], v[64:67]
	v_mfma_f32_16x16x32_bf16 v[148:151], v[172:175], v[188:191], v[148:151]
	v_mfma_f32_16x16x32_bf16 v[144:147], v[180:183], v[188:191], v[144:147]
	v_mfma_f32_16x16x32_bf16 v[124:127], v[172:175], v[196:199], v[124:127]
	v_mfma_f32_16x16x32_bf16 v[120:123], v[180:183], v[196:199], v[120:123]
	v_mfma_f32_16x16x32_bf16 v[108:111], v[172:175], v[204:207], v[108:111]
	v_mfma_f32_16x16x32_bf16 v[104:107], v[180:183], v[204:207], v[104:107]
	v_mfma_f32_16x16x32_bf16 v[68:71], v[172:175], v[228:231], v[68:71]
	v_mfma_f32_16x16x32_bf16 v[64:67], v[180:183], v[228:231], v[64:67]
	s_barrier
	ds_read_b128 v[184:187], v223 offset:49152
	ds_read_b128 v[188:191], v223 offset:50176
	ds_read_b128 v[192:195], v223 offset:51200
	ds_read_b128 v[196:199], v223 offset:52224
	ds_read_b128 v[200:203], v223 offset:53248
	ds_read_b128 v[204:207], v223 offset:54272
	ds_read_b128 v[224:227], v223 offset:55296
	ds_read_b128 v[228:231], v223 offset:56320
	s_or_b32 s13, s12, 0x4000
	s_mov_b32 m0, s34
	s_nop 0
	buffer_load_dwordx4 v220, s[48:51], s13 offen lds
	s_add_i32 s12, s12, 0x84000
	s_mov_b32 m0, s84
	s_nop 0
	buffer_load_dwordx4 v221, s[48:51], s13 offen lds
	s_mov_b32 m0, s87
	s_nop 0
	buffer_load_dwordx4 v220, s[48:51], s12 offen lds
	s_mov_b32 m0, s88
	s_nop 0
	buffer_load_dwordx4 v221, s[48:51], s12 offen lds
	s_mov_b32 m0, s85
	s_nop 0
	buffer_load_dwordx4 v220, s[64:67], s11 offen lds
	s_mov_b32 m0, s86
	s_nop 0
	buffer_load_dwordx4 v221, s[64:67], s11 offen lds
	s_waitcnt vmcnt(8)
	s_waitcnt lgkmcnt(0)
	s_barrier
	s_waitcnt lgkmcnt(7)
	v_mfma_f32_16x16x32_bf16 v[60:63], v[128:131], v[184:187], v[60:63]
	v_mfma_f32_16x16x32_bf16 v[56:59], v[152:155], v[184:187], v[56:59]
	s_waitcnt lgkmcnt(5)
	v_mfma_f32_16x16x32_bf16 v[44:47], v[128:131], v[192:195], v[44:47]
	v_mfma_f32_16x16x32_bf16 v[40:43], v[152:155], v[192:195], v[40:43]
	s_waitcnt lgkmcnt(3)
	v_mfma_f32_16x16x32_bf16 v[28:31], v[128:131], v[200:203], v[28:31]
	v_mfma_f32_16x16x32_bf16 v[24:27], v[152:155], v[200:203], v[24:27]
	s_waitcnt lgkmcnt(1)
	v_mfma_f32_16x16x32_bf16 v[12:15], v[128:131], v[224:227], v[12:15]
	v_mfma_f32_16x16x32_bf16 v[8:11], v[152:155], v[224:227], v[8:11]
	v_mfma_f32_16x16x32_bf16 v[60:63], v[140:143], v[188:191], v[60:63]
	v_mfma_f32_16x16x32_bf16 v[56:59], v[156:159], v[188:191], v[56:59]
	v_mfma_f32_16x16x32_bf16 v[44:47], v[140:143], v[196:199], v[44:47]
	v_mfma_f32_16x16x32_bf16 v[40:43], v[156:159], v[196:199], v[40:43]
	v_mfma_f32_16x16x32_bf16 v[28:31], v[140:143], v[204:207], v[28:31]
	v_mfma_f32_16x16x32_bf16 v[24:27], v[156:159], v[204:207], v[24:27]
	s_waitcnt lgkmcnt(0)
	v_mfma_f32_16x16x32_bf16 v[12:15], v[140:143], v[228:231], v[12:15]
	v_mfma_f32_16x16x32_bf16 v[8:11], v[156:159], v[228:231], v[8:11]
	v_mfma_f32_16x16x32_bf16 v[52:55], v[168:171], v[184:187], v[52:55]
	v_mfma_f32_16x16x32_bf16 v[48:51], v[176:179], v[184:187], v[48:51]
	v_mfma_f32_16x16x32_bf16 v[36:39], v[168:171], v[192:195], v[36:39]
	v_mfma_f32_16x16x32_bf16 v[32:35], v[176:179], v[192:195], v[32:35]
	v_mfma_f32_16x16x32_bf16 v[20:23], v[168:171], v[200:203], v[20:23]
	v_mfma_f32_16x16x32_bf16 v[16:19], v[176:179], v[200:203], v[16:19]
	v_mfma_f32_16x16x32_bf16 v[4:7], v[168:171], v[224:227], v[4:7]
	v_mfma_f32_16x16x32_bf16 v[0:3], v[176:179], v[224:227], v[0:3]
	v_mfma_f32_16x16x32_bf16 v[52:55], v[172:175], v[188:191], v[52:55]
	v_mfma_f32_16x16x32_bf16 v[48:51], v[180:183], v[188:191], v[48:51]
	v_mfma_f32_16x16x32_bf16 v[36:39], v[172:175], v[196:199], v[36:39]
	v_mfma_f32_16x16x32_bf16 v[32:35], v[180:183], v[196:199], v[32:35]
	v_mfma_f32_16x16x32_bf16 v[20:23], v[172:175], v[204:207], v[20:23]
	v_mfma_f32_16x16x32_bf16 v[16:19], v[180:183], v[204:207], v[16:19]
	v_mfma_f32_16x16x32_bf16 v[4:7], v[172:175], v[228:231], v[4:7]
	v_mfma_f32_16x16x32_bf16 v[0:3], v[180:183], v[228:231], v[0:3]
	s_barrier
	s_add_i32 s10, s10, 2
	s_add_i32 s8, s8, 0x8000
	s_add_i32 s9, s9, 0x8000
.LBB0_691:
	v_add_u32_e32 v156, 0x10000, v222
	v_add_u32_e32 v180, 0x14000, v222
	ds_read_b128 v[128:131], v156
	ds_read_b128 v[140:143], v156 offset:1024
	ds_read_b128 v[152:155], v156 offset:2048
	ds_read_b128 v[156:159], v156 offset:3072
	ds_read_b128 v[168:171], v180
	ds_read_b128 v[172:175], v180 offset:1024
	ds_read_b128 v[176:179], v180 offset:2048
	ds_read_b128 v[180:183], v180 offset:3072
	s_add_i32 s11, s8, 0xfff84000
	s_cmp_eq_u32 s10, 28
	s_cselect_b32 s13, s6, s11
	s_cselect_b32 s12, s7, s9
	s_or_b32 s11, s13, 0x4000
	ds_read_b128 v[184:187], v223
	ds_read_b128 v[188:191], v223 offset:1024
	ds_read_b128 v[192:195], v223 offset:2048
	ds_read_b128 v[196:199], v223 offset:3072
	ds_read_b128 v[200:203], v223 offset:4096
	ds_read_b128 v[204:207], v223 offset:5120
	ds_read_b128 v[224:227], v223 offset:6144
	ds_read_b128 v[228:231], v223 offset:7168
	s_mov_b32 m0, s89
	s_nop 0
	buffer_load_dwordx4 v220, s[64:67], s8 offen lds
	s_mov_b32 m0, s91
	s_nop 0
	buffer_load_dwordx4 v221, s[64:67], s8 offen lds
	s_waitcnt vmcnt(8)
	s_waitcnt lgkmcnt(0)
	s_barrier
	s_waitcnt lgkmcnt(7)
	v_mfma_f32_16x16x32_bf16 v[164:167], v[128:131], v[184:187], v[164:167]
	v_mfma_f32_16x16x32_bf16 v[160:163], v[152:155], v[184:187], v[160:163]
	s_waitcnt lgkmcnt(5)
	v_mfma_f32_16x16x32_bf16 v[136:139], v[128:131], v[192:195], v[136:139]
	v_mfma_f32_16x16x32_bf16 v[132:135], v[152:155], v[192:195], v[132:135]
	s_waitcnt lgkmcnt(3)
	v_mfma_f32_16x16x32_bf16 v[116:119], v[128:131], v[200:203], v[116:119]
	v_mfma_f32_16x16x32_bf16 v[112:115], v[152:155], v[200:203], v[112:115]
	s_waitcnt lgkmcnt(1)
	v_mfma_f32_16x16x32_bf16 v[76:79], v[128:131], v[224:227], v[76:79]
	v_mfma_f32_16x16x32_bf16 v[72:75], v[152:155], v[224:227], v[72:75]
	v_mfma_f32_16x16x32_bf16 v[164:167], v[140:143], v[188:191], v[164:167]
	v_mfma_f32_16x16x32_bf16 v[160:163], v[156:159], v[188:191], v[160:163]
	v_mfma_f32_16x16x32_bf16 v[136:139], v[140:143], v[196:199], v[136:139]
	v_mfma_f32_16x16x32_bf16 v[132:135], v[156:159], v[196:199], v[132:135]
	v_mfma_f32_16x16x32_bf16 v[116:119], v[140:143], v[204:207], v[116:119]
	v_mfma_f32_16x16x32_bf16 v[112:115], v[156:159], v[204:207], v[112:115]
	s_waitcnt lgkmcnt(0)
	v_mfma_f32_16x16x32_bf16 v[76:79], v[140:143], v[228:231], v[76:79]
	v_mfma_f32_16x16x32_bf16 v[72:75], v[156:159], v[228:231], v[72:75]
	v_mfma_f32_16x16x32_bf16 v[148:151], v[168:171], v[184:187], v[148:151]
	v_mfma_f32_16x16x32_bf16 v[144:147], v[176:179], v[184:187], v[144:147]
	v_mfma_f32_16x16x32_bf16 v[124:127], v[168:171], v[192:195], v[124:127]
	v_mfma_f32_16x16x32_bf16 v[120:123], v[176:179], v[192:195], v[120:123]
	v_mfma_f32_16x16x32_bf16 v[108:111], v[168:171], v[200:203], v[108:111]
	v_mfma_f32_16x16x32_bf16 v[104:107], v[176:179], v[200:203], v[104:107]
	v_mfma_f32_16x16x32_bf16 v[68:71], v[168:171], v[224:227], v[68:71]
	v_mfma_f32_16x16x32_bf16 v[64:67], v[176:179], v[224:227], v[64:67]
	v_mfma_f32_16x16x32_bf16 v[148:151], v[172:175], v[188:191], v[148:151]
	v_mfma_f32_16x16x32_bf16 v[144:147], v[180:183], v[188:191], v[144:147]
	v_mfma_f32_16x16x32_bf16 v[124:127], v[172:175], v[196:199], v[124:127]
	v_mfma_f32_16x16x32_bf16 v[120:123], v[180:183], v[196:199], v[120:123]
	v_mfma_f32_16x16x32_bf16 v[108:111], v[172:175], v[204:207], v[108:111]
	v_mfma_f32_16x16x32_bf16 v[104:107], v[180:183], v[204:207], v[104:107]
	v_mfma_f32_16x16x32_bf16 v[68:71], v[172:175], v[228:231], v[68:71]
	v_mfma_f32_16x16x32_bf16 v[64:67], v[180:183], v[228:231], v[64:67]
	s_barrier
	ds_read_b128 v[184:187], v223 offset:16384
	ds_read_b128 v[188:191], v223 offset:17408
	ds_read_b128 v[192:195], v223 offset:18432
	ds_read_b128 v[196:199], v223 offset:19456
	ds_read_b128 v[200:203], v223 offset:20480
	ds_read_b128 v[204:207], v223 offset:21504
	ds_read_b128 v[224:227], v223 offset:22528
	ds_read_b128 v[228:231], v223 offset:23552
	s_mov_b32 m0, s55
	s_nop 0
	buffer_load_dwordx4 v220, s[48:51], s12 offen lds
	s_add_i32 s14, s12, 0x80000
	s_mov_b32 m0, s76
	s_nop 0
	buffer_load_dwordx4 v221, s[48:51], s12 offen lds
	s_mov_b32 m0, s77
	s_nop 0
	buffer_load_dwordx4 v220, s[48:51], s14 offen lds
	s_mov_b32 m0, s78
	s_nop 0
	buffer_load_dwordx4 v221, s[48:51], s14 offen lds
	s_mov_b32 m0, s31
	s_nop 0
	buffer_load_dwordx4 v220, s[64:67], s13 offen lds
	s_mov_b32 m0, s79
	s_nop 0
	buffer_load_dwordx4 v221, s[64:67], s13 offen lds
	s_waitcnt vmcnt(8)
	s_waitcnt lgkmcnt(0)
	s_barrier
	s_waitcnt lgkmcnt(7)
	v_mfma_f32_16x16x32_bf16 v[60:63], v[128:131], v[184:187], v[60:63]
	v_mfma_f32_16x16x32_bf16 v[56:59], v[152:155], v[184:187], v[56:59]
	s_waitcnt lgkmcnt(5)
	v_mfma_f32_16x16x32_bf16 v[44:47], v[128:131], v[192:195], v[44:47]
	v_mfma_f32_16x16x32_bf16 v[40:43], v[152:155], v[192:195], v[40:43]
	s_waitcnt lgkmcnt(3)
	v_mfma_f32_16x16x32_bf16 v[28:31], v[128:131], v[200:203], v[28:31]
	v_mfma_f32_16x16x32_bf16 v[24:27], v[152:155], v[200:203], v[24:27]
	s_waitcnt lgkmcnt(1)
	v_mfma_f32_16x16x32_bf16 v[12:15], v[128:131], v[224:227], v[12:15]
	v_mfma_f32_16x16x32_bf16 v[8:11], v[152:155], v[224:227], v[8:11]
	v_mfma_f32_16x16x32_bf16 v[60:63], v[140:143], v[188:191], v[60:63]
	v_mfma_f32_16x16x32_bf16 v[56:59], v[156:159], v[188:191], v[56:59]
	v_mfma_f32_16x16x32_bf16 v[44:47], v[140:143], v[196:199], v[44:47]
	v_mfma_f32_16x16x32_bf16 v[40:43], v[156:159], v[196:199], v[40:43]
	v_mfma_f32_16x16x32_bf16 v[28:31], v[140:143], v[204:207], v[28:31]
	v_mfma_f32_16x16x32_bf16 v[24:27], v[156:159], v[204:207], v[24:27]
	s_waitcnt lgkmcnt(0)
	v_mfma_f32_16x16x32_bf16 v[12:15], v[140:143], v[228:231], v[12:15]
	v_mfma_f32_16x16x32_bf16 v[8:11], v[156:159], v[228:231], v[8:11]
	v_mfma_f32_16x16x32_bf16 v[52:55], v[168:171], v[184:187], v[52:55]
	v_mfma_f32_16x16x32_bf16 v[48:51], v[176:179], v[184:187], v[48:51]
	v_mfma_f32_16x16x32_bf16 v[36:39], v[168:171], v[192:195], v[36:39]
	v_mfma_f32_16x16x32_bf16 v[32:35], v[176:179], v[192:195], v[32:35]
	v_mfma_f32_16x16x32_bf16 v[20:23], v[168:171], v[200:203], v[20:23]
	v_mfma_f32_16x16x32_bf16 v[16:19], v[176:179], v[200:203], v[16:19]
	v_mfma_f32_16x16x32_bf16 v[4:7], v[168:171], v[224:227], v[4:7]
	v_mfma_f32_16x16x32_bf16 v[0:3], v[176:179], v[224:227], v[0:3]
	v_mfma_f32_16x16x32_bf16 v[52:55], v[172:175], v[188:191], v[52:55]
	v_mfma_f32_16x16x32_bf16 v[48:51], v[180:183], v[188:191], v[48:51]
	v_mfma_f32_16x16x32_bf16 v[36:39], v[172:175], v[196:199], v[36:39]
	v_mfma_f32_16x16x32_bf16 v[32:35], v[180:183], v[196:199], v[32:35]
	v_mfma_f32_16x16x32_bf16 v[20:23], v[172:175], v[204:207], v[20:23]
	v_mfma_f32_16x16x32_bf16 v[16:19], v[180:183], v[204:207], v[16:19]
	v_mfma_f32_16x16x32_bf16 v[4:7], v[172:175], v[228:231], v[4:7]
	v_mfma_f32_16x16x32_bf16 v[0:3], v[180:183], v[228:231], v[0:3]
	s_barrier
	v_add_u32_e32 v156, 0x18000, v222
	v_add_u32_e32 v180, 0x1c000, v222
	ds_read_b128 v[128:131], v156
	ds_read_b128 v[140:143], v156 offset:1024
	ds_read_b128 v[152:155], v156 offset:2048
	ds_read_b128 v[156:159], v156 offset:3072
	ds_read_b128 v[168:171], v180
	ds_read_b128 v[172:175], v180 offset:1024
	ds_read_b128 v[176:179], v180 offset:2048
	ds_read_b128 v[180:183], v180 offset:3072
	ds_read_b128 v[184:187], v223 offset:32768
	ds_read_b128 v[188:191], v223 offset:33792
	ds_read_b128 v[192:195], v223 offset:34816
	ds_read_b128 v[196:199], v223 offset:35840
	ds_read_b128 v[200:203], v223 offset:36864
	ds_read_b128 v[204:207], v223 offset:37888
	ds_read_b128 v[224:227], v223 offset:38912
	ds_read_b128 v[228:231], v223 offset:39936
	s_add_i32 s13, s13, 0x80000
	s_mov_b32 m0, s82
	s_nop 0
	buffer_load_dwordx4 v220, s[64:67], s13 offen lds
	s_mov_b32 m0, s83
	s_nop 0
	buffer_load_dwordx4 v221, s[64:67], s13 offen lds
	s_waitcnt vmcnt(8)
	s_waitcnt lgkmcnt(0)
	s_barrier
	s_waitcnt lgkmcnt(7)
	v_mfma_f32_16x16x32_bf16 v[164:167], v[128:131], v[184:187], v[164:167]
	v_mfma_f32_16x16x32_bf16 v[160:163], v[152:155], v[184:187], v[160:163]
	s_waitcnt lgkmcnt(5)
	v_mfma_f32_16x16x32_bf16 v[136:139], v[128:131], v[192:195], v[136:139]
	v_mfma_f32_16x16x32_bf16 v[132:135], v[152:155], v[192:195], v[132:135]
	s_waitcnt lgkmcnt(3)
	v_mfma_f32_16x16x32_bf16 v[116:119], v[128:131], v[200:203], v[116:119]
	v_mfma_f32_16x16x32_bf16 v[112:115], v[152:155], v[200:203], v[112:115]
	s_waitcnt lgkmcnt(1)
	v_mfma_f32_16x16x32_bf16 v[76:79], v[128:131], v[224:227], v[76:79]
	v_mfma_f32_16x16x32_bf16 v[72:75], v[152:155], v[224:227], v[72:75]
	v_mfma_f32_16x16x32_bf16 v[164:167], v[140:143], v[188:191], v[164:167]
	v_mfma_f32_16x16x32_bf16 v[160:163], v[156:159], v[188:191], v[160:163]
	v_mfma_f32_16x16x32_bf16 v[136:139], v[140:143], v[196:199], v[136:139]
	v_mfma_f32_16x16x32_bf16 v[132:135], v[156:159], v[196:199], v[132:135]
	v_mfma_f32_16x16x32_bf16 v[116:119], v[140:143], v[204:207], v[116:119]
	v_mfma_f32_16x16x32_bf16 v[112:115], v[156:159], v[204:207], v[112:115]
	s_waitcnt lgkmcnt(0)
	v_mfma_f32_16x16x32_bf16 v[76:79], v[140:143], v[228:231], v[76:79]
	v_mfma_f32_16x16x32_bf16 v[72:75], v[156:159], v[228:231], v[72:75]
	v_mfma_f32_16x16x32_bf16 v[148:151], v[168:171], v[184:187], v[148:151]
	v_mfma_f32_16x16x32_bf16 v[144:147], v[176:179], v[184:187], v[144:147]
	v_mfma_f32_16x16x32_bf16 v[124:127], v[168:171], v[192:195], v[124:127]
	v_mfma_f32_16x16x32_bf16 v[120:123], v[176:179], v[192:195], v[120:123]
	v_mfma_f32_16x16x32_bf16 v[108:111], v[168:171], v[200:203], v[108:111]
	v_mfma_f32_16x16x32_bf16 v[104:107], v[176:179], v[200:203], v[104:107]
	v_mfma_f32_16x16x32_bf16 v[68:71], v[168:171], v[224:227], v[68:71]
	v_mfma_f32_16x16x32_bf16 v[64:67], v[176:179], v[224:227], v[64:67]
	v_mfma_f32_16x16x32_bf16 v[148:151], v[172:175], v[188:191], v[148:151]
	v_mfma_f32_16x16x32_bf16 v[144:147], v[180:183], v[188:191], v[144:147]
	v_mfma_f32_16x16x32_bf16 v[124:127], v[172:175], v[196:199], v[124:127]
	v_mfma_f32_16x16x32_bf16 v[120:123], v[180:183], v[196:199], v[120:123]
	v_mfma_f32_16x16x32_bf16 v[108:111], v[172:175], v[204:207], v[108:111]
	v_mfma_f32_16x16x32_bf16 v[104:107], v[180:183], v[204:207], v[104:107]
	v_mfma_f32_16x16x32_bf16 v[68:71], v[172:175], v[228:231], v[68:71]
	v_mfma_f32_16x16x32_bf16 v[64:67], v[180:183], v[228:231], v[64:67]
	s_barrier
	ds_read_b128 v[184:187], v223 offset:49152
	ds_read_b128 v[188:191], v223 offset:50176
	ds_read_b128 v[192:195], v223 offset:51200
	ds_read_b128 v[196:199], v223 offset:52224
	ds_read_b128 v[200:203], v223 offset:53248
	ds_read_b128 v[204:207], v223 offset:54272
	ds_read_b128 v[224:227], v223 offset:55296
	ds_read_b128 v[228:231], v223 offset:56320
	s_or_b32 s13, s12, 0x4000
	s_mov_b32 m0, s34
	s_nop 0
	buffer_load_dwordx4 v220, s[48:51], s13 offen lds
	s_add_i32 s12, s12, 0x84000
	s_mov_b32 m0, s84
	s_nop 0
	buffer_load_dwordx4 v221, s[48:51], s13 offen lds
	s_mov_b32 m0, s87
	s_nop 0
	buffer_load_dwordx4 v220, s[48:51], s12 offen lds
	s_mov_b32 m0, s88
	s_nop 0
	buffer_load_dwordx4 v221, s[48:51], s12 offen lds
	s_mov_b32 m0, s85
	s_nop 0
	buffer_load_dwordx4 v220, s[64:67], s11 offen lds
	s_mov_b32 m0, s86
	s_nop 0
	buffer_load_dwordx4 v221, s[64:67], s11 offen lds
	s_waitcnt vmcnt(8)
	s_waitcnt lgkmcnt(0)
	s_barrier
	s_waitcnt lgkmcnt(7)
	v_mfma_f32_16x16x32_bf16 v[60:63], v[128:131], v[184:187], v[60:63]
	v_mfma_f32_16x16x32_bf16 v[56:59], v[152:155], v[184:187], v[56:59]
	s_waitcnt lgkmcnt(5)
	v_mfma_f32_16x16x32_bf16 v[44:47], v[128:131], v[192:195], v[44:47]
	v_mfma_f32_16x16x32_bf16 v[40:43], v[152:155], v[192:195], v[40:43]
	s_waitcnt lgkmcnt(3)
	v_mfma_f32_16x16x32_bf16 v[28:31], v[128:131], v[200:203], v[28:31]
	v_mfma_f32_16x16x32_bf16 v[24:27], v[152:155], v[200:203], v[24:27]
	s_waitcnt lgkmcnt(1)
	v_mfma_f32_16x16x32_bf16 v[12:15], v[128:131], v[224:227], v[12:15]
	v_mfma_f32_16x16x32_bf16 v[8:11], v[152:155], v[224:227], v[8:11]
	v_mfma_f32_16x16x32_bf16 v[60:63], v[140:143], v[188:191], v[60:63]
	v_mfma_f32_16x16x32_bf16 v[56:59], v[156:159], v[188:191], v[56:59]
	v_mfma_f32_16x16x32_bf16 v[44:47], v[140:143], v[196:199], v[44:47]
	v_mfma_f32_16x16x32_bf16 v[40:43], v[156:159], v[196:199], v[40:43]
	v_mfma_f32_16x16x32_bf16 v[28:31], v[140:143], v[204:207], v[28:31]
	v_mfma_f32_16x16x32_bf16 v[24:27], v[156:159], v[204:207], v[24:27]
	s_waitcnt lgkmcnt(0)
	v_mfma_f32_16x16x32_bf16 v[12:15], v[140:143], v[228:231], v[12:15]
	v_mfma_f32_16x16x32_bf16 v[8:11], v[156:159], v[228:231], v[8:11]
	v_mfma_f32_16x16x32_bf16 v[52:55], v[168:171], v[184:187], v[52:55]
	v_mfma_f32_16x16x32_bf16 v[48:51], v[176:179], v[184:187], v[48:51]
	v_mfma_f32_16x16x32_bf16 v[36:39], v[168:171], v[192:195], v[36:39]
	v_mfma_f32_16x16x32_bf16 v[32:35], v[176:179], v[192:195], v[32:35]
	v_mfma_f32_16x16x32_bf16 v[20:23], v[168:171], v[200:203], v[20:23]
	v_mfma_f32_16x16x32_bf16 v[16:19], v[176:179], v[200:203], v[16:19]
	v_mfma_f32_16x16x32_bf16 v[4:7], v[168:171], v[224:227], v[4:7]
	v_mfma_f32_16x16x32_bf16 v[0:3], v[176:179], v[224:227], v[0:3]
	v_mfma_f32_16x16x32_bf16 v[52:55], v[172:175], v[188:191], v[52:55]
	v_mfma_f32_16x16x32_bf16 v[48:51], v[180:183], v[188:191], v[48:51]
	v_mfma_f32_16x16x32_bf16 v[36:39], v[172:175], v[196:199], v[36:39]
	v_mfma_f32_16x16x32_bf16 v[32:35], v[180:183], v[196:199], v[32:35]
	v_mfma_f32_16x16x32_bf16 v[20:23], v[172:175], v[204:207], v[20:23]
	v_mfma_f32_16x16x32_bf16 v[16:19], v[180:183], v[204:207], v[16:19]
	v_mfma_f32_16x16x32_bf16 v[4:7], v[172:175], v[228:231], v[4:7]
	v_mfma_f32_16x16x32_bf16 v[0:3], v[180:183], v[228:231], v[0:3]
	s_barrier
	s_add_i32 s10, s10, 2
	s_add_i32 s8, s8, 0x8000
	s_add_i32 s9, s9, 0x8000
	s_cmp_gt_u32 s10, 29
	s_cbranch_scc0 .LBB0_691

.Lnb_p5:
	s_add_i32 s53, s37, 0xfff84000
	s_cmp_eq_u32 s52, 28
	s_cselect_b32 s56, s4, s53
	s_cselect_b32 s55, s5, s51
	s_or_b32 s53, s56, 0x4000
	s_mov_b32 m0, s41
	s_nop 0
	buffer_load_dwordx4 v166, s[24:27], s37 offen lds
	s_mov_b32 m0, s42
	s_nop 0
	buffer_load_dwordx4 v167, s[24:27], s37 offen lds
	s_waitcnt vmcnt(24)
	s_waitcnt lgkmcnt(0)
	s_barrier
	s_waitcnt lgkmcnt(7)
	v_mfma_f32_16x16x32_bf16 v[148:151], v[152:155], v[190:193], 0
	v_mfma_f32_16x16x32_bf16 v[140:143], v[160:163], v[190:193], 0
	s_waitcnt lgkmcnt(5)
	v_mfma_f32_16x16x32_bf16 v[132:135], v[152:155], v[198:201], 0
	v_mfma_f32_16x16x32_bf16 v[124:127], v[160:163], v[198:201], 0
	s_waitcnt lgkmcnt(3)
	v_mfma_f32_16x16x32_bf16 v[116:119], v[152:155], v[220:223], 0
	v_mfma_f32_16x16x32_bf16 v[108:111], v[160:163], v[220:223], 0
	s_waitcnt lgkmcnt(1)
	v_mfma_f32_16x16x32_bf16 v[76:79], v[152:155], v[228:231], 0
	v_mfma_f32_16x16x32_bf16 v[68:71], v[160:163], v[228:231], 0
	v_mfma_f32_16x16x32_bf16 v[148:151], v[156:159], v[194:197], v[148:151]
	v_mfma_f32_16x16x32_bf16 v[140:143], v[170:173], v[194:197], v[140:143]
	v_mfma_f32_16x16x32_bf16 v[132:135], v[156:159], v[202:205], v[132:135]
	v_mfma_f32_16x16x32_bf16 v[124:127], v[170:173], v[202:205], v[124:127]
	v_mfma_f32_16x16x32_bf16 v[116:119], v[156:159], v[224:227], v[116:119]
	v_mfma_f32_16x16x32_bf16 v[108:111], v[170:173], v[224:227], v[108:111]
	s_waitcnt lgkmcnt(0)
	v_mfma_f32_16x16x32_bf16 v[76:79], v[156:159], v[240:243], v[76:79]
	v_mfma_f32_16x16x32_bf16 v[68:71], v[170:173], v[240:243], v[68:71]
	v_mfma_f32_16x16x32_bf16 v[144:147], v[174:177], v[190:193], 0
	v_mfma_f32_16x16x32_bf16 v[136:139], v[182:185], v[190:193], 0
	v_mfma_f32_16x16x32_bf16 v[128:131], v[174:177], v[198:201], 0
	v_mfma_f32_16x16x32_bf16 v[120:123], v[182:185], v[198:201], 0
	v_mfma_f32_16x16x32_bf16 v[112:115], v[174:177], v[220:223], 0
	v_mfma_f32_16x16x32_bf16 v[104:107], v[182:185], v[220:223], 0
	v_mfma_f32_16x16x32_bf16 v[72:75], v[174:177], v[228:231], 0
	v_mfma_f32_16x16x32_bf16 v[64:67], v[182:185], v[228:231], 0
	v_mfma_f32_16x16x32_bf16 v[144:147], v[178:181], v[194:197], v[144:147]
	v_mfma_f32_16x16x32_bf16 v[136:139], v[186:189], v[194:197], v[136:139]
	v_mfma_f32_16x16x32_bf16 v[128:131], v[178:181], v[202:205], v[128:131]
	v_mfma_f32_16x16x32_bf16 v[120:123], v[186:189], v[202:205], v[120:123]
	v_mfma_f32_16x16x32_bf16 v[112:115], v[178:181], v[224:227], v[112:115]
	v_mfma_f32_16x16x32_bf16 v[104:107], v[186:189], v[224:227], v[104:107]
	v_mfma_f32_16x16x32_bf16 v[72:75], v[178:181], v[240:243], v[72:75]
	v_mfma_f32_16x16x32_bf16 v[64:67], v[186:189], v[240:243], v[64:67]
	s_barrier
	ds_read_b128 v[190:193], v169 offset:16384
	ds_read_b128 v[194:197], v169 offset:17408
	ds_read_b128 v[198:201], v169 offset:18432
	ds_read_b128 v[202:205], v169 offset:19456
	ds_read_b128 v[220:223], v169 offset:20480
	ds_read_b128 v[224:227], v169 offset:21504
	ds_read_b128 v[228:231], v169 offset:22528
	ds_read_b128 v[240:243], v169 offset:23552
	s_mov_b32 m0, s7
	s_nop 0
	buffer_load_dwordx4 v166, s[28:31], s55 offen lds
	s_add_i32 s57, s55, 0x80000
	s_mov_b32 m0, s8
	s_nop 0
	buffer_load_dwordx4 v167, s[28:31], s55 offen lds
	s_mov_b32 m0, s9
	s_nop 0
	buffer_load_dwordx4 v166, s[28:31], s57 offen lds
	s_mov_b32 m0, s10
	s_nop 0
	buffer_load_dwordx4 v167, s[28:31], s57 offen lds
	s_mov_b32 m0, s6
	s_nop 0
	buffer_load_dwordx4 v166, s[24:27], s56 offen lds
	s_mov_b32 m0, s11
	s_nop 0
	buffer_load_dwordx4 v167, s[24:27], s56 offen lds
	s_waitcnt vmcnt(24)
	s_waitcnt lgkmcnt(0)
	s_barrier
	s_waitcnt lgkmcnt(7)
	v_mfma_f32_16x16x32_bf16 v[60:63], v[152:155], v[190:193], 0
	v_mfma_f32_16x16x32_bf16 v[52:55], v[160:163], v[190:193], 0
	s_waitcnt lgkmcnt(5)
	v_mfma_f32_16x16x32_bf16 v[44:47], v[152:155], v[198:201], 0
	v_mfma_f32_16x16x32_bf16 v[36:39], v[160:163], v[198:201], 0
	s_waitcnt lgkmcnt(3)
	v_mfma_f32_16x16x32_bf16 v[28:31], v[152:155], v[220:223], 0
	v_mfma_f32_16x16x32_bf16 v[20:23], v[160:163], v[220:223], 0
	s_waitcnt lgkmcnt(1)
	v_mfma_f32_16x16x32_bf16 v[12:15], v[152:155], v[228:231], 0
	v_mfma_f32_16x16x32_bf16 v[4:7], v[160:163], v[228:231], 0
	v_mfma_f32_16x16x32_bf16 v[60:63], v[156:159], v[194:197], v[60:63]
	v_mfma_f32_16x16x32_bf16 v[52:55], v[170:173], v[194:197], v[52:55]
	v_mfma_f32_16x16x32_bf16 v[44:47], v[156:159], v[202:205], v[44:47]
	v_mfma_f32_16x16x32_bf16 v[36:39], v[170:173], v[202:205], v[36:39]
	v_mfma_f32_16x16x32_bf16 v[28:31], v[156:159], v[224:227], v[28:31]
	v_mfma_f32_16x16x32_bf16 v[20:23], v[170:173], v[224:227], v[20:23]
	s_waitcnt lgkmcnt(0)
	v_mfma_f32_16x16x32_bf16 v[12:15], v[156:159], v[240:243], v[12:15]
	v_mfma_f32_16x16x32_bf16 v[4:7], v[170:173], v[240:243], v[4:7]
	v_mfma_f32_16x16x32_bf16 v[56:59], v[174:177], v[190:193], 0
	v_mfma_f32_16x16x32_bf16 v[48:51], v[182:185], v[190:193], 0
	v_mfma_f32_16x16x32_bf16 v[40:43], v[174:177], v[198:201], 0
	v_mfma_f32_16x16x32_bf16 v[32:35], v[182:185], v[198:201], 0
	v_mfma_f32_16x16x32_bf16 v[24:27], v[174:177], v[220:223], 0
	v_mfma_f32_16x16x32_bf16 v[16:19], v[182:185], v[220:223], 0
	v_mfma_f32_16x16x32_bf16 v[8:11], v[174:177], v[228:231], 0
	v_mfma_f32_16x16x32_bf16 v[0:3], v[182:185], v[228:231], 0
	v_mfma_f32_16x16x32_bf16 v[56:59], v[178:181], v[194:197], v[56:59]
	v_mfma_f32_16x16x32_bf16 v[48:51], v[186:189], v[194:197], v[48:51]
	v_mfma_f32_16x16x32_bf16 v[40:43], v[178:181], v[202:205], v[40:43]
	v_mfma_f32_16x16x32_bf16 v[32:35], v[186:189], v[202:205], v[32:35]
	v_mfma_f32_16x16x32_bf16 v[24:27], v[178:181], v[224:227], v[24:27]
	v_mfma_f32_16x16x32_bf16 v[16:19], v[186:189], v[224:227], v[16:19]
	v_mfma_f32_16x16x32_bf16 v[8:11], v[178:181], v[240:243], v[8:11]
	v_mfma_f32_16x16x32_bf16 v[0:3], v[186:189], v[240:243], v[0:3]
	s_barrier
	v_add_u32_e32 v164, 0x18000, v168
	ds_read_b128 v[152:155], v164
	ds_read_b128 v[156:159], v164 offset:1024
	ds_read_b128 v[160:163], v164 offset:2048
	ds_read_b128 v[170:173], v164 offset:3072
	v_add_u32_e32 v164, 0x1c000, v168
	ds_read_b128 v[174:177], v164
	ds_read_b128 v[178:181], v164 offset:1024
	ds_read_b128 v[182:185], v164 offset:2048
	ds_read_b128 v[186:189], v164 offset:3072
	ds_read_b128 v[190:193], v169 offset:32768
	ds_read_b128 v[194:197], v169 offset:33792
	ds_read_b128 v[198:201], v169 offset:34816
	ds_read_b128 v[202:205], v169 offset:35840
	ds_read_b128 v[220:223], v169 offset:36864
	ds_read_b128 v[224:227], v169 offset:37888
	ds_read_b128 v[228:231], v169 offset:38912
	ds_read_b128 v[240:243], v169 offset:39936
	s_add_i32 s56, s56, 0x80000
	s_mov_b32 m0, s12
	s_nop 0
	buffer_load_dwordx4 v166, s[24:27], s56 offen lds
	s_mov_b32 m0, s13
	s_nop 0
	buffer_load_dwordx4 v167, s[24:27], s56 offen lds
	s_waitcnt vmcnt(8)
	s_waitcnt lgkmcnt(0)
	s_barrier
	s_waitcnt lgkmcnt(7)
	v_mfma_f32_16x16x32_bf16 v[148:151], v[152:155], v[190:193], v[148:151]
	v_mfma_f32_16x16x32_bf16 v[140:143], v[160:163], v[190:193], v[140:143]
	s_waitcnt lgkmcnt(5)
	v_mfma_f32_16x16x32_bf16 v[132:135], v[152:155], v[198:201], v[132:135]
	v_mfma_f32_16x16x32_bf16 v[124:127], v[160:163], v[198:201], v[124:127]
	s_waitcnt lgkmcnt(3)
	v_mfma_f32_16x16x32_bf16 v[116:119], v[152:155], v[220:223], v[116:119]
	v_mfma_f32_16x16x32_bf16 v[108:111], v[160:163], v[220:223], v[108:111]
	s_waitcnt lgkmcnt(1)
	v_mfma_f32_16x16x32_bf16 v[76:79], v[152:155], v[228:231], v[76:79]
	v_mfma_f32_16x16x32_bf16 v[68:71], v[160:163], v[228:231], v[68:71]
	v_mfma_f32_16x16x32_bf16 v[148:151], v[156:159], v[194:197], v[148:151]
	v_mfma_f32_16x16x32_bf16 v[140:143], v[170:173], v[194:197], v[140:143]
	v_mfma_f32_16x16x32_bf16 v[132:135], v[156:159], v[202:205], v[132:135]
	v_mfma_f32_16x16x32_bf16 v[124:127], v[170:173], v[202:205], v[124:127]
	v_mfma_f32_16x16x32_bf16 v[116:119], v[156:159], v[224:227], v[116:119]
	v_mfma_f32_16x16x32_bf16 v[108:111], v[170:173], v[224:227], v[108:111]
	s_waitcnt lgkmcnt(0)
	v_mfma_f32_16x16x32_bf16 v[76:79], v[156:159], v[240:243], v[76:79]
	v_mfma_f32_16x16x32_bf16 v[68:71], v[170:173], v[240:243], v[68:71]
	v_mfma_f32_16x16x32_bf16 v[144:147], v[174:177], v[190:193], v[144:147]
	v_mfma_f32_16x16x32_bf16 v[136:139], v[182:185], v[190:193], v[136:139]
	v_mfma_f32_16x16x32_bf16 v[128:131], v[174:177], v[198:201], v[128:131]
	v_mfma_f32_16x16x32_bf16 v[120:123], v[182:185], v[198:201], v[120:123]
	v_mfma_f32_16x16x32_bf16 v[112:115], v[174:177], v[220:223], v[112:115]
	v_mfma_f32_16x16x32_bf16 v[104:107], v[182:185], v[220:223], v[104:107]
	v_mfma_f32_16x16x32_bf16 v[72:75], v[174:177], v[228:231], v[72:75]
	v_mfma_f32_16x16x32_bf16 v[64:67], v[182:185], v[228:231], v[64:67]
	v_mfma_f32_16x16x32_bf16 v[144:147], v[178:181], v[194:197], v[144:147]
	v_mfma_f32_16x16x32_bf16 v[136:139], v[186:189], v[194:197], v[136:139]
	v_mfma_f32_16x16x32_bf16 v[128:131], v[178:181], v[202:205], v[128:131]
	v_mfma_f32_16x16x32_bf16 v[120:123], v[186:189], v[202:205], v[120:123]
	v_mfma_f32_16x16x32_bf16 v[112:115], v[178:181], v[224:227], v[112:115]
	v_mfma_f32_16x16x32_bf16 v[104:107], v[186:189], v[224:227], v[104:107]
	v_mfma_f32_16x16x32_bf16 v[72:75], v[178:181], v[240:243], v[72:75]
	v_mfma_f32_16x16x32_bf16 v[64:67], v[186:189], v[240:243], v[64:67]
	s_barrier
	ds_read_b128 v[190:193], v169 offset:49152
	ds_read_b128 v[194:197], v169 offset:50176
	ds_read_b128 v[198:201], v169 offset:51200
	ds_read_b128 v[202:205], v169 offset:52224
	ds_read_b128 v[220:223], v169 offset:53248
	ds_read_b128 v[224:227], v169 offset:54272
	ds_read_b128 v[228:231], v169 offset:55296
	ds_read_b128 v[240:243], v169 offset:56320
	s_or_b32 s56, s55, 0x4000
	s_mov_b32 m0, s16
	s_nop 0
	buffer_load_dwordx4 v166, s[28:31], s56 offen lds
	s_add_i32 s55, s55, 0x84000
	s_mov_b32 m0, s17
	s_nop 0
	buffer_load_dwordx4 v167, s[28:31], s56 offen lds
	s_mov_b32 m0, s34
	s_nop 0
	buffer_load_dwordx4 v166, s[28:31], s55 offen lds
	s_mov_b32 m0, s40
	s_nop 0
	buffer_load_dwordx4 v167, s[28:31], s55 offen lds
	s_mov_b32 m0, s18
	s_nop 0
	buffer_load_dwordx4 v166, s[24:27], s53 offen lds
	s_mov_b32 m0, s19
	s_nop 0
	buffer_load_dwordx4 v167, s[24:27], s53 offen lds
	s_waitcnt vmcnt(8)
	s_waitcnt lgkmcnt(0)
	s_barrier
	s_waitcnt lgkmcnt(7)
	v_mfma_f32_16x16x32_bf16 v[60:63], v[152:155], v[190:193], v[60:63]
	v_mfma_f32_16x16x32_bf16 v[52:55], v[160:163], v[190:193], v[52:55]
	s_waitcnt lgkmcnt(5)
	v_mfma_f32_16x16x32_bf16 v[44:47], v[152:155], v[198:201], v[44:47]
	v_mfma_f32_16x16x32_bf16 v[36:39], v[160:163], v[198:201], v[36:39]
	s_waitcnt lgkmcnt(3)
	v_mfma_f32_16x16x32_bf16 v[28:31], v[152:155], v[220:223], v[28:31]
	v_mfma_f32_16x16x32_bf16 v[20:23], v[160:163], v[220:223], v[20:23]
	s_waitcnt lgkmcnt(1)
	v_mfma_f32_16x16x32_bf16 v[12:15], v[152:155], v[228:231], v[12:15]
	v_mfma_f32_16x16x32_bf16 v[4:7], v[160:163], v[228:231], v[4:7]
	v_mfma_f32_16x16x32_bf16 v[60:63], v[156:159], v[194:197], v[60:63]
	v_mfma_f32_16x16x32_bf16 v[52:55], v[170:173], v[194:197], v[52:55]
	v_mfma_f32_16x16x32_bf16 v[44:47], v[156:159], v[202:205], v[44:47]
	v_mfma_f32_16x16x32_bf16 v[36:39], v[170:173], v[202:205], v[36:39]
	v_mfma_f32_16x16x32_bf16 v[28:31], v[156:159], v[224:227], v[28:31]
	v_mfma_f32_16x16x32_bf16 v[20:23], v[170:173], v[224:227], v[20:23]
	s_waitcnt lgkmcnt(0)
	v_mfma_f32_16x16x32_bf16 v[12:15], v[156:159], v[240:243], v[12:15]
	v_mfma_f32_16x16x32_bf16 v[4:7], v[170:173], v[240:243], v[4:7]
	v_mfma_f32_16x16x32_bf16 v[56:59], v[174:177], v[190:193], v[56:59]
	v_mfma_f32_16x16x32_bf16 v[48:51], v[182:185], v[190:193], v[48:51]
	v_mfma_f32_16x16x32_bf16 v[40:43], v[174:177], v[198:201], v[40:43]
	v_mfma_f32_16x16x32_bf16 v[32:35], v[182:185], v[198:201], v[32:35]
	v_mfma_f32_16x16x32_bf16 v[24:27], v[174:177], v[220:223], v[24:27]
	v_mfma_f32_16x16x32_bf16 v[16:19], v[182:185], v[220:223], v[16:19]
	v_mfma_f32_16x16x32_bf16 v[8:11], v[174:177], v[228:231], v[8:11]
	v_mfma_f32_16x16x32_bf16 v[0:3], v[182:185], v[228:231], v[0:3]
	v_mfma_f32_16x16x32_bf16 v[56:59], v[178:181], v[194:197], v[56:59]
	v_mfma_f32_16x16x32_bf16 v[48:51], v[186:189], v[194:197], v[48:51]
	v_mfma_f32_16x16x32_bf16 v[40:43], v[178:181], v[202:205], v[40:43]
	v_mfma_f32_16x16x32_bf16 v[32:35], v[186:189], v[202:205], v[32:35]
	v_mfma_f32_16x16x32_bf16 v[24:27], v[178:181], v[224:227], v[24:27]
	v_mfma_f32_16x16x32_bf16 v[16:19], v[186:189], v[224:227], v[16:19]
	v_mfma_f32_16x16x32_bf16 v[8:11], v[178:181], v[240:243], v[8:11]
	v_mfma_f32_16x16x32_bf16 v[0:3], v[186:189], v[240:243], v[0:3]
	s_barrier
	s_add_i32 s52, s52, 2
	s_add_i32 s37, s37, 0x8000
	s_add_i32 s51, s51, 0x8000
.LBB0_795:
	v_add_u32_e32 v164, 0x10000, v168
	ds_read_b128 v[152:155], v164
	ds_read_b128 v[156:159], v164 offset:1024
	ds_read_b128 v[160:163], v164 offset:2048
	ds_read_b128 v[170:173], v164 offset:3072
	v_add_u32_e32 v164, 0x14000, v168
	ds_read_b128 v[174:177], v164
	ds_read_b128 v[178:181], v164 offset:1024
	ds_read_b128 v[182:185], v164 offset:2048
	ds_read_b128 v[186:189], v164 offset:3072
	s_add_i32 s53, s37, 0xfff84000
	s_cmp_eq_u32 s52, 28
	s_cselect_b32 s56, s4, s53
	s_cselect_b32 s55, s5, s51
	s_or_b32 s53, s56, 0x4000
	ds_read_b128 v[190:193], v169
	ds_read_b128 v[194:197], v169 offset:1024
	ds_read_b128 v[198:201], v169 offset:2048
	ds_read_b128 v[202:205], v169 offset:3072
	ds_read_b128 v[220:223], v169 offset:4096
	ds_read_b128 v[224:227], v169 offset:5120
	ds_read_b128 v[228:231], v169 offset:6144
	ds_read_b128 v[240:243], v169 offset:7168
	s_mov_b32 m0, s41
	s_nop 0
	buffer_load_dwordx4 v166, s[24:27], s37 offen lds
	s_mov_b32 m0, s42
	s_nop 0
	buffer_load_dwordx4 v167, s[24:27], s37 offen lds
	s_waitcnt vmcnt(8)
	s_waitcnt lgkmcnt(0)
	s_barrier
	s_waitcnt lgkmcnt(7)
	v_mfma_f32_16x16x32_bf16 v[148:151], v[152:155], v[190:193], v[148:151]
	v_mfma_f32_16x16x32_bf16 v[140:143], v[160:163], v[190:193], v[140:143]
	s_waitcnt lgkmcnt(5)
	v_mfma_f32_16x16x32_bf16 v[132:135], v[152:155], v[198:201], v[132:135]
	v_mfma_f32_16x16x32_bf16 v[124:127], v[160:163], v[198:201], v[124:127]
	s_waitcnt lgkmcnt(3)
	v_mfma_f32_16x16x32_bf16 v[116:119], v[152:155], v[220:223], v[116:119]
	v_mfma_f32_16x16x32_bf16 v[108:111], v[160:163], v[220:223], v[108:111]
	s_waitcnt lgkmcnt(1)
	v_mfma_f32_16x16x32_bf16 v[76:79], v[152:155], v[228:231], v[76:79]
	v_mfma_f32_16x16x32_bf16 v[68:71], v[160:163], v[228:231], v[68:71]
	v_mfma_f32_16x16x32_bf16 v[148:151], v[156:159], v[194:197], v[148:151]
	v_mfma_f32_16x16x32_bf16 v[140:143], v[170:173], v[194:197], v[140:143]
	v_mfma_f32_16x16x32_bf16 v[132:135], v[156:159], v[202:205], v[132:135]
	v_mfma_f32_16x16x32_bf16 v[124:127], v[170:173], v[202:205], v[124:127]
	v_mfma_f32_16x16x32_bf16 v[116:119], v[156:159], v[224:227], v[116:119]
	v_mfma_f32_16x16x32_bf16 v[108:111], v[170:173], v[224:227], v[108:111]
	s_waitcnt lgkmcnt(0)
	v_mfma_f32_16x16x32_bf16 v[76:79], v[156:159], v[240:243], v[76:79]
	v_mfma_f32_16x16x32_bf16 v[68:71], v[170:173], v[240:243], v[68:71]
	v_mfma_f32_16x16x32_bf16 v[144:147], v[174:177], v[190:193], v[144:147]
	v_mfma_f32_16x16x32_bf16 v[136:139], v[182:185], v[190:193], v[136:139]
	v_mfma_f32_16x16x32_bf16 v[128:131], v[174:177], v[198:201], v[128:131]
	v_mfma_f32_16x16x32_bf16 v[120:123], v[182:185], v[198:201], v[120:123]
	v_mfma_f32_16x16x32_bf16 v[112:115], v[174:177], v[220:223], v[112:115]
	v_mfma_f32_16x16x32_bf16 v[104:107], v[182:185], v[220:223], v[104:107]
	v_mfma_f32_16x16x32_bf16 v[72:75], v[174:177], v[228:231], v[72:75]
	v_mfma_f32_16x16x32_bf16 v[64:67], v[182:185], v[228:231], v[64:67]
	v_mfma_f32_16x16x32_bf16 v[144:147], v[178:181], v[194:197], v[144:147]
	v_mfma_f32_16x16x32_bf16 v[136:139], v[186:189], v[194:197], v[136:139]
	v_mfma_f32_16x16x32_bf16 v[128:131], v[178:181], v[202:205], v[128:131]
	v_mfma_f32_16x16x32_bf16 v[120:123], v[186:189], v[202:205], v[120:123]
	v_mfma_f32_16x16x32_bf16 v[112:115], v[178:181], v[224:227], v[112:115]
	v_mfma_f32_16x16x32_bf16 v[104:107], v[186:189], v[224:227], v[104:107]
	v_mfma_f32_16x16x32_bf16 v[72:75], v[178:181], v[240:243], v[72:75]
	v_mfma_f32_16x16x32_bf16 v[64:67], v[186:189], v[240:243], v[64:67]
	s_barrier
	ds_read_b128 v[190:193], v169 offset:16384
	ds_read_b128 v[194:197], v169 offset:17408
	ds_read_b128 v[198:201], v169 offset:18432
	ds_read_b128 v[202:205], v169 offset:19456
	ds_read_b128 v[220:223], v169 offset:20480
	ds_read_b128 v[224:227], v169 offset:21504
	ds_read_b128 v[228:231], v169 offset:22528
	ds_read_b128 v[240:243], v169 offset:23552
	s_mov_b32 m0, s7
	s_nop 0
	buffer_load_dwordx4 v166, s[28:31], s55 offen lds
	s_add_i32 s57, s55, 0x80000
	s_mov_b32 m0, s8
	s_nop 0
	buffer_load_dwordx4 v167, s[28:31], s55 offen lds
	s_mov_b32 m0, s9
	s_nop 0
	buffer_load_dwordx4 v166, s[28:31], s57 offen lds
	s_mov_b32 m0, s10
	s_nop 0
	buffer_load_dwordx4 v167, s[28:31], s57 offen lds
	s_mov_b32 m0, s6
	s_nop 0
	buffer_load_dwordx4 v166, s[24:27], s56 offen lds
	s_mov_b32 m0, s11
	s_nop 0
	buffer_load_dwordx4 v167, s[24:27], s56 offen lds
	s_waitcnt vmcnt(8)
	s_waitcnt lgkmcnt(0)
	s_barrier
	s_waitcnt lgkmcnt(7)
	v_mfma_f32_16x16x32_bf16 v[60:63], v[152:155], v[190:193], v[60:63]
	v_mfma_f32_16x16x32_bf16 v[52:55], v[160:163], v[190:193], v[52:55]
	s_waitcnt lgkmcnt(5)
	v_mfma_f32_16x16x32_bf16 v[44:47], v[152:155], v[198:201], v[44:47]
	v_mfma_f32_16x16x32_bf16 v[36:39], v[160:163], v[198:201], v[36:39]
	s_waitcnt lgkmcnt(3)
	v_mfma_f32_16x16x32_bf16 v[28:31], v[152:155], v[220:223], v[28:31]
	v_mfma_f32_16x16x32_bf16 v[20:23], v[160:163], v[220:223], v[20:23]
	s_waitcnt lgkmcnt(1)
	v_mfma_f32_16x16x32_bf16 v[12:15], v[152:155], v[228:231], v[12:15]
	v_mfma_f32_16x16x32_bf16 v[4:7], v[160:163], v[228:231], v[4:7]
	v_mfma_f32_16x16x32_bf16 v[60:63], v[156:159], v[194:197], v[60:63]
	v_mfma_f32_16x16x32_bf16 v[52:55], v[170:173], v[194:197], v[52:55]
	v_mfma_f32_16x16x32_bf16 v[44:47], v[156:159], v[202:205], v[44:47]
	v_mfma_f32_16x16x32_bf16 v[36:39], v[170:173], v[202:205], v[36:39]
	v_mfma_f32_16x16x32_bf16 v[28:31], v[156:159], v[224:227], v[28:31]
	v_mfma_f32_16x16x32_bf16 v[20:23], v[170:173], v[224:227], v[20:23]
	s_waitcnt lgkmcnt(0)
	v_mfma_f32_16x16x32_bf16 v[12:15], v[156:159], v[240:243], v[12:15]
	v_mfma_f32_16x16x32_bf16 v[4:7], v[170:173], v[240:243], v[4:7]
	v_mfma_f32_16x16x32_bf16 v[56:59], v[174:177], v[190:193], v[56:59]
	v_mfma_f32_16x16x32_bf16 v[48:51], v[182:185], v[190:193], v[48:51]
	v_mfma_f32_16x16x32_bf16 v[40:43], v[174:177], v[198:201], v[40:43]
	v_mfma_f32_16x16x32_bf16 v[32:35], v[182:185], v[198:201], v[32:35]
	v_mfma_f32_16x16x32_bf16 v[24:27], v[174:177], v[220:223], v[24:27]
	v_mfma_f32_16x16x32_bf16 v[16:19], v[182:185], v[220:223], v[16:19]
	v_mfma_f32_16x16x32_bf16 v[8:11], v[174:177], v[228:231], v[8:11]
	v_mfma_f32_16x16x32_bf16 v[0:3], v[182:185], v[228:231], v[0:3]
	v_mfma_f32_16x16x32_bf16 v[56:59], v[178:181], v[194:197], v[56:59]
	v_mfma_f32_16x16x32_bf16 v[48:51], v[186:189], v[194:197], v[48:51]
	v_mfma_f32_16x16x32_bf16 v[40:43], v[178:181], v[202:205], v[40:43]
	v_mfma_f32_16x16x32_bf16 v[32:35], v[186:189], v[202:205], v[32:35]
	v_mfma_f32_16x16x32_bf16 v[24:27], v[178:181], v[224:227], v[24:27]
	v_mfma_f32_16x16x32_bf16 v[16:19], v[186:189], v[224:227], v[16:19]
	v_mfma_f32_16x16x32_bf16 v[8:11], v[178:181], v[240:243], v[8:11]
	v_mfma_f32_16x16x32_bf16 v[0:3], v[186:189], v[240:243], v[0:3]
	s_barrier
	v_add_u32_e32 v164, 0x18000, v168
	ds_read_b128 v[152:155], v164
	ds_read_b128 v[156:159], v164 offset:1024
	ds_read_b128 v[160:163], v164 offset:2048
	ds_read_b128 v[170:173], v164 offset:3072
	v_add_u32_e32 v164, 0x1c000, v168
	ds_read_b128 v[174:177], v164
	ds_read_b128 v[178:181], v164 offset:1024
	ds_read_b128 v[182:185], v164 offset:2048
	ds_read_b128 v[186:189], v164 offset:3072
	ds_read_b128 v[190:193], v169 offset:32768
	ds_read_b128 v[194:197], v169 offset:33792
	ds_read_b128 v[198:201], v169 offset:34816
	ds_read_b128 v[202:205], v169 offset:35840
	ds_read_b128 v[220:223], v169 offset:36864
	ds_read_b128 v[224:227], v169 offset:37888
	ds_read_b128 v[228:231], v169 offset:38912
	ds_read_b128 v[240:243], v169 offset:39936
	s_add_i32 s56, s56, 0x80000
	s_mov_b32 m0, s12
	s_nop 0
	buffer_load_dwordx4 v166, s[24:27], s56 offen lds
	s_mov_b32 m0, s13
	s_nop 0
	buffer_load_dwordx4 v167, s[24:27], s56 offen lds
	s_waitcnt vmcnt(8)
	s_waitcnt lgkmcnt(0)
	s_barrier
	s_waitcnt lgkmcnt(7)
	v_mfma_f32_16x16x32_bf16 v[148:151], v[152:155], v[190:193], v[148:151]
	v_mfma_f32_16x16x32_bf16 v[140:143], v[160:163], v[190:193], v[140:143]
	s_waitcnt lgkmcnt(5)
	v_mfma_f32_16x16x32_bf16 v[132:135], v[152:155], v[198:201], v[132:135]
	v_mfma_f32_16x16x32_bf16 v[124:127], v[160:163], v[198:201], v[124:127]
	s_waitcnt lgkmcnt(3)
	v_mfma_f32_16x16x32_bf16 v[116:119], v[152:155], v[220:223], v[116:119]
	v_mfma_f32_16x16x32_bf16 v[108:111], v[160:163], v[220:223], v[108:111]
	s_waitcnt lgkmcnt(1)
	v_mfma_f32_16x16x32_bf16 v[76:79], v[152:155], v[228:231], v[76:79]
	v_mfma_f32_16x16x32_bf16 v[68:71], v[160:163], v[228:231], v[68:71]
	v_mfma_f32_16x16x32_bf16 v[148:151], v[156:159], v[194:197], v[148:151]
	v_mfma_f32_16x16x32_bf16 v[140:143], v[170:173], v[194:197], v[140:143]
	v_mfma_f32_16x16x32_bf16 v[132:135], v[156:159], v[202:205], v[132:135]
	v_mfma_f32_16x16x32_bf16 v[124:127], v[170:173], v[202:205], v[124:127]
	v_mfma_f32_16x16x32_bf16 v[116:119], v[156:159], v[224:227], v[116:119]
	v_mfma_f32_16x16x32_bf16 v[108:111], v[170:173], v[224:227], v[108:111]
	s_waitcnt lgkmcnt(0)
	v_mfma_f32_16x16x32_bf16 v[76:79], v[156:159], v[240:243], v[76:79]
	v_mfma_f32_16x16x32_bf16 v[68:71], v[170:173], v[240:243], v[68:71]
	v_mfma_f32_16x16x32_bf16 v[144:147], v[174:177], v[190:193], v[144:147]
	v_mfma_f32_16x16x32_bf16 v[136:139], v[182:185], v[190:193], v[136:139]
	v_mfma_f32_16x16x32_bf16 v[128:131], v[174:177], v[198:201], v[128:131]
	v_mfma_f32_16x16x32_bf16 v[120:123], v[182:185], v[198:201], v[120:123]
	v_mfma_f32_16x16x32_bf16 v[112:115], v[174:177], v[220:223], v[112:115]
	v_mfma_f32_16x16x32_bf16 v[104:107], v[182:185], v[220:223], v[104:107]
	v_mfma_f32_16x16x32_bf16 v[72:75], v[174:177], v[228:231], v[72:75]
	v_mfma_f32_16x16x32_bf16 v[64:67], v[182:185], v[228:231], v[64:67]
	v_mfma_f32_16x16x32_bf16 v[144:147], v[178:181], v[194:197], v[144:147]
	v_mfma_f32_16x16x32_bf16 v[136:139], v[186:189], v[194:197], v[136:139]
	v_mfma_f32_16x16x32_bf16 v[128:131], v[178:181], v[202:205], v[128:131]
	v_mfma_f32_16x16x32_bf16 v[120:123], v[186:189], v[202:205], v[120:123]
	v_mfma_f32_16x16x32_bf16 v[112:115], v[178:181], v[224:227], v[112:115]
	v_mfma_f32_16x16x32_bf16 v[104:107], v[186:189], v[224:227], v[104:107]
	v_mfma_f32_16x16x32_bf16 v[72:75], v[178:181], v[240:243], v[72:75]
	v_mfma_f32_16x16x32_bf16 v[64:67], v[186:189], v[240:243], v[64:67]
	s_barrier
	ds_read_b128 v[190:193], v169 offset:49152
	ds_read_b128 v[194:197], v169 offset:50176
	ds_read_b128 v[198:201], v169 offset:51200
	ds_read_b128 v[202:205], v169 offset:52224
	ds_read_b128 v[220:223], v169 offset:53248
	ds_read_b128 v[224:227], v169 offset:54272
	ds_read_b128 v[228:231], v169 offset:55296
	ds_read_b128 v[240:243], v169 offset:56320
	s_or_b32 s56, s55, 0x4000
	s_mov_b32 m0, s16
	s_nop 0
	buffer_load_dwordx4 v166, s[28:31], s56 offen lds
	s_add_i32 s55, s55, 0x84000
	s_mov_b32 m0, s17
	s_nop 0
	buffer_load_dwordx4 v167, s[28:31], s56 offen lds
	s_mov_b32 m0, s34
	s_nop 0
	buffer_load_dwordx4 v166, s[28:31], s55 offen lds
	s_mov_b32 m0, s40
	s_nop 0
	buffer_load_dwordx4 v167, s[28:31], s55 offen lds
	s_mov_b32 m0, s18
	s_nop 0
	buffer_load_dwordx4 v166, s[24:27], s53 offen lds
	s_mov_b32 m0, s19
	s_nop 0
	buffer_load_dwordx4 v167, s[24:27], s53 offen lds
	s_waitcnt vmcnt(8)
	s_waitcnt lgkmcnt(0)
	s_barrier
	s_waitcnt lgkmcnt(7)
	v_mfma_f32_16x16x32_bf16 v[60:63], v[152:155], v[190:193], v[60:63]
	v_mfma_f32_16x16x32_bf16 v[52:55], v[160:163], v[190:193], v[52:55]
	s_waitcnt lgkmcnt(5)
	v_mfma_f32_16x16x32_bf16 v[44:47], v[152:155], v[198:201], v[44:47]
	v_mfma_f32_16x16x32_bf16 v[36:39], v[160:163], v[198:201], v[36:39]
	s_waitcnt lgkmcnt(3)
	v_mfma_f32_16x16x32_bf16 v[28:31], v[152:155], v[220:223], v[28:31]
	v_mfma_f32_16x16x32_bf16 v[20:23], v[160:163], v[220:223], v[20:23]
	s_waitcnt lgkmcnt(1)
	v_mfma_f32_16x16x32_bf16 v[12:15], v[152:155], v[228:231], v[12:15]
	v_mfma_f32_16x16x32_bf16 v[4:7], v[160:163], v[228:231], v[4:7]
	v_mfma_f32_16x16x32_bf16 v[60:63], v[156:159], v[194:197], v[60:63]
	v_mfma_f32_16x16x32_bf16 v[52:55], v[170:173], v[194:197], v[52:55]
	v_mfma_f32_16x16x32_bf16 v[44:47], v[156:159], v[202:205], v[44:47]
	v_mfma_f32_16x16x32_bf16 v[36:39], v[170:173], v[202:205], v[36:39]
	v_mfma_f32_16x16x32_bf16 v[28:31], v[156:159], v[224:227], v[28:31]
	v_mfma_f32_16x16x32_bf16 v[20:23], v[170:173], v[224:227], v[20:23]
	s_waitcnt lgkmcnt(0)
	v_mfma_f32_16x16x32_bf16 v[12:15], v[156:159], v[240:243], v[12:15]
	v_mfma_f32_16x16x32_bf16 v[4:7], v[170:173], v[240:243], v[4:7]
	v_mfma_f32_16x16x32_bf16 v[56:59], v[174:177], v[190:193], v[56:59]
	v_mfma_f32_16x16x32_bf16 v[48:51], v[182:185], v[190:193], v[48:51]
	v_mfma_f32_16x16x32_bf16 v[40:43], v[174:177], v[198:201], v[40:43]
	v_mfma_f32_16x16x32_bf16 v[32:35], v[182:185], v[198:201], v[32:35]
	v_mfma_f32_16x16x32_bf16 v[24:27], v[174:177], v[220:223], v[24:27]
	v_mfma_f32_16x16x32_bf16 v[16:19], v[182:185], v[220:223], v[16:19]
	v_mfma_f32_16x16x32_bf16 v[8:11], v[174:177], v[228:231], v[8:11]
	v_mfma_f32_16x16x32_bf16 v[0:3], v[182:185], v[228:231], v[0:3]
	v_mfma_f32_16x16x32_bf16 v[56:59], v[178:181], v[194:197], v[56:59]
	v_mfma_f32_16x16x32_bf16 v[48:51], v[186:189], v[194:197], v[48:51]
	v_mfma_f32_16x16x32_bf16 v[40:43], v[178:181], v[202:205], v[40:43]
	v_mfma_f32_16x16x32_bf16 v[32:35], v[186:189], v[202:205], v[32:35]
	v_mfma_f32_16x16x32_bf16 v[24:27], v[178:181], v[224:227], v[24:27]
	v_mfma_f32_16x16x32_bf16 v[16:19], v[186:189], v[224:227], v[16:19]
	v_mfma_f32_16x16x32_bf16 v[8:11], v[178:181], v[240:243], v[8:11]
	v_mfma_f32_16x16x32_bf16 v[0:3], v[186:189], v[240:243], v[0:3]
	s_barrier
	s_add_i32 s52, s52, 2
	s_add_i32 s37, s37, 0x8000
	s_add_i32 s51, s51, 0x8000
	s_cmp_gt_u32 s52, 29
	s_cbranch_scc0 .LBB0_795

.Lnb_p6:
	s_add_i32 s11, s8, 0xffea4000
	s_cmpk_eq_i32 s10, 0x54
	s_cselect_b32 s13, s6, s11
	s_cselect_b32 s12, s7, s9
	s_or_b32 s11, s13, 0x4000
	s_mov_b32 m0, s87
	s_nop 0
	buffer_load_dwordx4 v220, s[20:23], s8 offen lds
	s_mov_b32 m0, s89
	s_nop 0
	buffer_load_dwordx4 v221, s[20:23], s8 offen lds
	s_waitcnt vmcnt(24)
	s_waitcnt lgkmcnt(0)
	s_barrier
	s_waitcnt lgkmcnt(7)
	v_mfma_f32_16x16x32_bf16 v[164:167], v[128:131], v[184:187], 0
	v_mfma_f32_16x16x32_bf16 v[160:163], v[152:155], v[184:187], 0
	s_waitcnt lgkmcnt(5)
	v_mfma_f32_16x16x32_bf16 v[136:139], v[128:131], v[192:195], 0
	v_mfma_f32_16x16x32_bf16 v[132:135], v[152:155], v[192:195], 0
	s_waitcnt lgkmcnt(3)
	v_mfma_f32_16x16x32_bf16 v[116:119], v[128:131], v[200:203], 0
	v_mfma_f32_16x16x32_bf16 v[112:115], v[152:155], v[200:203], 0
	s_waitcnt lgkmcnt(1)
	v_mfma_f32_16x16x32_bf16 v[76:79], v[128:131], v[224:227], 0
	v_mfma_f32_16x16x32_bf16 v[72:75], v[152:155], v[224:227], 0
	v_mfma_f32_16x16x32_bf16 v[164:167], v[140:143], v[188:191], v[164:167]
	v_mfma_f32_16x16x32_bf16 v[160:163], v[156:159], v[188:191], v[160:163]
	v_mfma_f32_16x16x32_bf16 v[136:139], v[140:143], v[196:199], v[136:139]
	v_mfma_f32_16x16x32_bf16 v[132:135], v[156:159], v[196:199], v[132:135]
	v_mfma_f32_16x16x32_bf16 v[116:119], v[140:143], v[204:207], v[116:119]
	v_mfma_f32_16x16x32_bf16 v[112:115], v[156:159], v[204:207], v[112:115]
	s_waitcnt lgkmcnt(0)
	v_mfma_f32_16x16x32_bf16 v[76:79], v[140:143], v[228:231], v[76:79]
	v_mfma_f32_16x16x32_bf16 v[72:75], v[156:159], v[228:231], v[72:75]
	v_mfma_f32_16x16x32_bf16 v[148:151], v[168:171], v[184:187], 0
	v_mfma_f32_16x16x32_bf16 v[144:147], v[176:179], v[184:187], 0
	v_mfma_f32_16x16x32_bf16 v[124:127], v[168:171], v[192:195], 0
	v_mfma_f32_16x16x32_bf16 v[120:123], v[176:179], v[192:195], 0
	v_mfma_f32_16x16x32_bf16 v[108:111], v[168:171], v[200:203], 0
	v_mfma_f32_16x16x32_bf16 v[104:107], v[176:179], v[200:203], 0
	v_mfma_f32_16x16x32_bf16 v[68:71], v[168:171], v[224:227], 0
	v_mfma_f32_16x16x32_bf16 v[64:67], v[176:179], v[224:227], 0
	v_mfma_f32_16x16x32_bf16 v[148:151], v[172:175], v[188:191], v[148:151]
	v_mfma_f32_16x16x32_bf16 v[144:147], v[180:183], v[188:191], v[144:147]
	v_mfma_f32_16x16x32_bf16 v[124:127], v[172:175], v[196:199], v[124:127]
	v_mfma_f32_16x16x32_bf16 v[120:123], v[180:183], v[196:199], v[120:123]
	v_mfma_f32_16x16x32_bf16 v[108:111], v[172:175], v[204:207], v[108:111]
	v_mfma_f32_16x16x32_bf16 v[104:107], v[180:183], v[204:207], v[104:107]
	v_mfma_f32_16x16x32_bf16 v[68:71], v[172:175], v[228:231], v[68:71]
	v_mfma_f32_16x16x32_bf16 v[64:67], v[180:183], v[228:231], v[64:67]
	s_barrier
	ds_read_b128 v[184:187], v223 offset:16384
	ds_read_b128 v[188:191], v223 offset:17408
	ds_read_b128 v[192:195], v223 offset:18432
	ds_read_b128 v[196:199], v223 offset:19456
	ds_read_b128 v[200:203], v223 offset:20480
	ds_read_b128 v[204:207], v223 offset:21504
	ds_read_b128 v[224:227], v223 offset:22528
	ds_read_b128 v[228:231], v223 offset:23552
	s_mov_b32 m0, s51
	s_nop 0
	buffer_load_dwordx4 v220, s[52:55], s12 offen lds
	s_add_i32 s14, s12, 0x160000
	s_mov_b32 m0, s74
	s_nop 0
	buffer_load_dwordx4 v221, s[52:55], s12 offen lds
	s_mov_b32 m0, s75
	s_nop 0
	buffer_load_dwordx4 v220, s[52:55], s14 offen lds
	s_mov_b32 m0, s76
	s_nop 0
	buffer_load_dwordx4 v221, s[52:55], s14 offen lds
	s_mov_b32 m0, s31
	s_nop 0
	buffer_load_dwordx4 v220, s[20:23], s13 offen lds
	s_mov_b32 m0, s77
	s_nop 0
	buffer_load_dwordx4 v221, s[20:23], s13 offen lds
	s_waitcnt vmcnt(24)
	s_waitcnt lgkmcnt(0)
	s_barrier
	s_waitcnt lgkmcnt(7)
	v_mfma_f32_16x16x32_bf16 v[60:63], v[128:131], v[184:187], 0
	v_mfma_f32_16x16x32_bf16 v[56:59], v[152:155], v[184:187], 0
	s_waitcnt lgkmcnt(5)
	v_mfma_f32_16x16x32_bf16 v[44:47], v[128:131], v[192:195], 0
	v_mfma_f32_16x16x32_bf16 v[40:43], v[152:155], v[192:195], 0
	s_waitcnt lgkmcnt(3)
	v_mfma_f32_16x16x32_bf16 v[28:31], v[128:131], v[200:203], 0
	v_mfma_f32_16x16x32_bf16 v[24:27], v[152:155], v[200:203], 0
	s_waitcnt lgkmcnt(1)
	v_mfma_f32_16x16x32_bf16 v[12:15], v[128:131], v[224:227], 0
	v_mfma_f32_16x16x32_bf16 v[8:11], v[152:155], v[224:227], 0
	v_mfma_f32_16x16x32_bf16 v[60:63], v[140:143], v[188:191], v[60:63]
	v_mfma_f32_16x16x32_bf16 v[56:59], v[156:159], v[188:191], v[56:59]
	v_mfma_f32_16x16x32_bf16 v[44:47], v[140:143], v[196:199], v[44:47]
	v_mfma_f32_16x16x32_bf16 v[40:43], v[156:159], v[196:199], v[40:43]
	v_mfma_f32_16x16x32_bf16 v[28:31], v[140:143], v[204:207], v[28:31]
	v_mfma_f32_16x16x32_bf16 v[24:27], v[156:159], v[204:207], v[24:27]
	s_waitcnt lgkmcnt(0)
	v_mfma_f32_16x16x32_bf16 v[12:15], v[140:143], v[228:231], v[12:15]
	v_mfma_f32_16x16x32_bf16 v[8:11], v[156:159], v[228:231], v[8:11]
	v_mfma_f32_16x16x32_bf16 v[52:55], v[168:171], v[184:187], 0
	v_mfma_f32_16x16x32_bf16 v[48:51], v[176:179], v[184:187], 0
	v_mfma_f32_16x16x32_bf16 v[36:39], v[168:171], v[192:195], 0
	v_mfma_f32_16x16x32_bf16 v[32:35], v[176:179], v[192:195], 0
	v_mfma_f32_16x16x32_bf16 v[20:23], v[168:171], v[200:203], 0
	v_mfma_f32_16x16x32_bf16 v[16:19], v[176:179], v[200:203], 0
	v_mfma_f32_16x16x32_bf16 v[4:7], v[168:171], v[224:227], 0
	v_mfma_f32_16x16x32_bf16 v[0:3], v[176:179], v[224:227], 0
	v_mfma_f32_16x16x32_bf16 v[52:55], v[172:175], v[188:191], v[52:55]
	v_mfma_f32_16x16x32_bf16 v[48:51], v[180:183], v[188:191], v[48:51]
	v_mfma_f32_16x16x32_bf16 v[36:39], v[172:175], v[196:199], v[36:39]
	v_mfma_f32_16x16x32_bf16 v[32:35], v[180:183], v[196:199], v[32:35]
	v_mfma_f32_16x16x32_bf16 v[20:23], v[172:175], v[204:207], v[20:23]
	v_mfma_f32_16x16x32_bf16 v[16:19], v[180:183], v[204:207], v[16:19]
	v_mfma_f32_16x16x32_bf16 v[4:7], v[172:175], v[228:231], v[4:7]
	v_mfma_f32_16x16x32_bf16 v[0:3], v[180:183], v[228:231], v[0:3]
	s_barrier
	v_add_u32_e32 v156, 0x18000, v222
	v_add_u32_e32 v180, 0x1c000, v222
	ds_read_b128 v[128:131], v156
	ds_read_b128 v[140:143], v156 offset:1024
	ds_read_b128 v[152:155], v156 offset:2048
	ds_read_b128 v[156:159], v156 offset:3072
	ds_read_b128 v[168:171], v180
	ds_read_b128 v[172:175], v180 offset:1024
	ds_read_b128 v[176:179], v180 offset:2048
	ds_read_b128 v[180:183], v180 offset:3072
	ds_read_b128 v[184:187], v223 offset:32768
	ds_read_b128 v[188:191], v223 offset:33792
	ds_read_b128 v[192:195], v223 offset:34816
	ds_read_b128 v[196:199], v223 offset:35840
	ds_read_b128 v[200:203], v223 offset:36864
	ds_read_b128 v[204:207], v223 offset:37888
	ds_read_b128 v[224:227], v223 offset:38912
	ds_read_b128 v[228:231], v223 offset:39936
	s_add_i32 s13, s13, 0x160000
	s_mov_b32 m0, s78
	s_nop 0
	buffer_load_dwordx4 v220, s[20:23], s13 offen lds
	s_mov_b32 m0, s79
	s_nop 0
	buffer_load_dwordx4 v221, s[20:23], s13 offen lds
	s_waitcnt vmcnt(8)
	s_waitcnt lgkmcnt(0)
	s_barrier
	s_waitcnt lgkmcnt(7)
	v_mfma_f32_16x16x32_bf16 v[164:167], v[128:131], v[184:187], v[164:167]
	v_mfma_f32_16x16x32_bf16 v[160:163], v[152:155], v[184:187], v[160:163]
	s_waitcnt lgkmcnt(5)
	v_mfma_f32_16x16x32_bf16 v[136:139], v[128:131], v[192:195], v[136:139]
	v_mfma_f32_16x16x32_bf16 v[132:135], v[152:155], v[192:195], v[132:135]
	s_waitcnt lgkmcnt(3)
	v_mfma_f32_16x16x32_bf16 v[116:119], v[128:131], v[200:203], v[116:119]
	v_mfma_f32_16x16x32_bf16 v[112:115], v[152:155], v[200:203], v[112:115]
	s_waitcnt lgkmcnt(1)
	v_mfma_f32_16x16x32_bf16 v[76:79], v[128:131], v[224:227], v[76:79]
	v_mfma_f32_16x16x32_bf16 v[72:75], v[152:155], v[224:227], v[72:75]
	v_mfma_f32_16x16x32_bf16 v[164:167], v[140:143], v[188:191], v[164:167]
	v_mfma_f32_16x16x32_bf16 v[160:163], v[156:159], v[188:191], v[160:163]
	v_mfma_f32_16x16x32_bf16 v[136:139], v[140:143], v[196:199], v[136:139]
	v_mfma_f32_16x16x32_bf16 v[132:135], v[156:159], v[196:199], v[132:135]
	v_mfma_f32_16x16x32_bf16 v[116:119], v[140:143], v[204:207], v[116:119]
	v_mfma_f32_16x16x32_bf16 v[112:115], v[156:159], v[204:207], v[112:115]
	s_waitcnt lgkmcnt(0)
	v_mfma_f32_16x16x32_bf16 v[76:79], v[140:143], v[228:231], v[76:79]
	v_mfma_f32_16x16x32_bf16 v[72:75], v[156:159], v[228:231], v[72:75]
	v_mfma_f32_16x16x32_bf16 v[148:151], v[168:171], v[184:187], v[148:151]
	v_mfma_f32_16x16x32_bf16 v[144:147], v[176:179], v[184:187], v[144:147]
	v_mfma_f32_16x16x32_bf16 v[124:127], v[168:171], v[192:195], v[124:127]
	v_mfma_f32_16x16x32_bf16 v[120:123], v[176:179], v[192:195], v[120:123]
	v_mfma_f32_16x16x32_bf16 v[108:111], v[168:171], v[200:203], v[108:111]
	v_mfma_f32_16x16x32_bf16 v[104:107], v[176:179], v[200:203], v[104:107]
	v_mfma_f32_16x16x32_bf16 v[68:71], v[168:171], v[224:227], v[68:71]
	v_mfma_f32_16x16x32_bf16 v[64:67], v[176:179], v[224:227], v[64:67]
	v_mfma_f32_16x16x32_bf16 v[148:151], v[172:175], v[188:191], v[148:151]
	v_mfma_f32_16x16x32_bf16 v[144:147], v[180:183], v[188:191], v[144:147]
	v_mfma_f32_16x16x32_bf16 v[124:127], v[172:175], v[196:199], v[124:127]
	v_mfma_f32_16x16x32_bf16 v[120:123], v[180:183], v[196:199], v[120:123]
	v_mfma_f32_16x16x32_bf16 v[108:111], v[172:175], v[204:207], v[108:111]
	v_mfma_f32_16x16x32_bf16 v[104:107], v[180:183], v[204:207], v[104:107]
	v_mfma_f32_16x16x32_bf16 v[68:71], v[172:175], v[228:231], v[68:71]
	v_mfma_f32_16x16x32_bf16 v[64:67], v[180:183], v[228:231], v[64:67]
	s_barrier
	ds_read_b128 v[184:187], v223 offset:49152
	ds_read_b128 v[188:191], v223 offset:50176
	ds_read_b128 v[192:195], v223 offset:51200
	ds_read_b128 v[196:199], v223 offset:52224
	ds_read_b128 v[200:203], v223 offset:53248
	ds_read_b128 v[204:207], v223 offset:54272
	ds_read_b128 v[224:227], v223 offset:55296
	ds_read_b128 v[228:231], v223 offset:56320
	s_or_b32 s13, s12, 0x4000
	s_mov_b32 m0, s34
	s_nop 0
	buffer_load_dwordx4 v220, s[52:55], s13 offen lds
	s_add_i32 s12, s12, 0x164000
	s_mov_b32 m0, s82
	s_nop 0
	buffer_load_dwordx4 v221, s[52:55], s13 offen lds
	s_mov_b32 m0, s85
	s_nop 0
	buffer_load_dwordx4 v220, s[52:55], s12 offen lds
	s_mov_b32 m0, s86
	s_nop 0
	buffer_load_dwordx4 v221, s[52:55], s12 offen lds
	s_mov_b32 m0, s83
	s_nop 0
	buffer_load_dwordx4 v220, s[20:23], s11 offen lds
	s_mov_b32 m0, s84
	s_nop 0
	buffer_load_dwordx4 v221, s[20:23], s11 offen lds
	s_waitcnt vmcnt(8)
	s_waitcnt lgkmcnt(0)
	s_barrier
	s_waitcnt lgkmcnt(7)
	v_mfma_f32_16x16x32_bf16 v[60:63], v[128:131], v[184:187], v[60:63]
	v_mfma_f32_16x16x32_bf16 v[56:59], v[152:155], v[184:187], v[56:59]
	s_waitcnt lgkmcnt(5)
	v_mfma_f32_16x16x32_bf16 v[44:47], v[128:131], v[192:195], v[44:47]
	v_mfma_f32_16x16x32_bf16 v[40:43], v[152:155], v[192:195], v[40:43]
	s_waitcnt lgkmcnt(3)
	v_mfma_f32_16x16x32_bf16 v[28:31], v[128:131], v[200:203], v[28:31]
	v_mfma_f32_16x16x32_bf16 v[24:27], v[152:155], v[200:203], v[24:27]
	s_waitcnt lgkmcnt(1)
	v_mfma_f32_16x16x32_bf16 v[12:15], v[128:131], v[224:227], v[12:15]
	v_mfma_f32_16x16x32_bf16 v[8:11], v[152:155], v[224:227], v[8:11]
	v_mfma_f32_16x16x32_bf16 v[60:63], v[140:143], v[188:191], v[60:63]
	v_mfma_f32_16x16x32_bf16 v[56:59], v[156:159], v[188:191], v[56:59]
	v_mfma_f32_16x16x32_bf16 v[44:47], v[140:143], v[196:199], v[44:47]
	v_mfma_f32_16x16x32_bf16 v[40:43], v[156:159], v[196:199], v[40:43]
	v_mfma_f32_16x16x32_bf16 v[28:31], v[140:143], v[204:207], v[28:31]
	v_mfma_f32_16x16x32_bf16 v[24:27], v[156:159], v[204:207], v[24:27]
	s_waitcnt lgkmcnt(0)
	v_mfma_f32_16x16x32_bf16 v[12:15], v[140:143], v[228:231], v[12:15]
	v_mfma_f32_16x16x32_bf16 v[8:11], v[156:159], v[228:231], v[8:11]
	v_mfma_f32_16x16x32_bf16 v[52:55], v[168:171], v[184:187], v[52:55]
	v_mfma_f32_16x16x32_bf16 v[48:51], v[176:179], v[184:187], v[48:51]
	v_mfma_f32_16x16x32_bf16 v[36:39], v[168:171], v[192:195], v[36:39]
	v_mfma_f32_16x16x32_bf16 v[32:35], v[176:179], v[192:195], v[32:35]
	v_mfma_f32_16x16x32_bf16 v[20:23], v[168:171], v[200:203], v[20:23]
	v_mfma_f32_16x16x32_bf16 v[16:19], v[176:179], v[200:203], v[16:19]
	v_mfma_f32_16x16x32_bf16 v[4:7], v[168:171], v[224:227], v[4:7]
	v_mfma_f32_16x16x32_bf16 v[0:3], v[176:179], v[224:227], v[0:3]
	v_mfma_f32_16x16x32_bf16 v[52:55], v[172:175], v[188:191], v[52:55]
	v_mfma_f32_16x16x32_bf16 v[48:51], v[180:183], v[188:191], v[48:51]
	v_mfma_f32_16x16x32_bf16 v[36:39], v[172:175], v[196:199], v[36:39]
	v_mfma_f32_16x16x32_bf16 v[32:35], v[180:183], v[196:199], v[32:35]
	v_mfma_f32_16x16x32_bf16 v[20:23], v[172:175], v[204:207], v[20:23]
	v_mfma_f32_16x16x32_bf16 v[16:19], v[180:183], v[204:207], v[16:19]
	v_mfma_f32_16x16x32_bf16 v[4:7], v[172:175], v[228:231], v[4:7]
	v_mfma_f32_16x16x32_bf16 v[0:3], v[180:183], v[228:231], v[0:3]
	s_barrier
	s_add_i32 s10, s10, 2
	s_add_i32 s8, s8, 0x8000
	s_add_i32 s9, s9, 0x8000
.LBB0_885:
	v_add_u32_e32 v156, 0x10000, v222
	v_add_u32_e32 v180, 0x14000, v222
	ds_read_b128 v[128:131], v156
	ds_read_b128 v[140:143], v156 offset:1024
	ds_read_b128 v[152:155], v156 offset:2048
	ds_read_b128 v[156:159], v156 offset:3072
	ds_read_b128 v[168:171], v180
	ds_read_b128 v[172:175], v180 offset:1024
	ds_read_b128 v[176:179], v180 offset:2048
	ds_read_b128 v[180:183], v180 offset:3072
	s_add_i32 s11, s8, 0xffea4000
	s_cmpk_eq_i32 s10, 0x54
	s_cselect_b32 s13, s6, s11
	s_cselect_b32 s12, s7, s9
	s_or_b32 s11, s13, 0x4000
	ds_read_b128 v[184:187], v223
	ds_read_b128 v[188:191], v223 offset:1024
	ds_read_b128 v[192:195], v223 offset:2048
	ds_read_b128 v[196:199], v223 offset:3072
	ds_read_b128 v[200:203], v223 offset:4096
	ds_read_b128 v[204:207], v223 offset:5120
	ds_read_b128 v[224:227], v223 offset:6144
	ds_read_b128 v[228:231], v223 offset:7168
	s_mov_b32 m0, s87
	s_nop 0
	buffer_load_dwordx4 v220, s[20:23], s8 offen lds
	s_mov_b32 m0, s89
	s_nop 0
	buffer_load_dwordx4 v221, s[20:23], s8 offen lds
	s_waitcnt vmcnt(8)
	s_waitcnt lgkmcnt(0)
	s_barrier
	s_waitcnt lgkmcnt(7)
	v_mfma_f32_16x16x32_bf16 v[164:167], v[128:131], v[184:187], v[164:167]
	v_mfma_f32_16x16x32_bf16 v[160:163], v[152:155], v[184:187], v[160:163]
	s_waitcnt lgkmcnt(5)
	v_mfma_f32_16x16x32_bf16 v[136:139], v[128:131], v[192:195], v[136:139]
	v_mfma_f32_16x16x32_bf16 v[132:135], v[152:155], v[192:195], v[132:135]
	s_waitcnt lgkmcnt(3)
	v_mfma_f32_16x16x32_bf16 v[116:119], v[128:131], v[200:203], v[116:119]
	v_mfma_f32_16x16x32_bf16 v[112:115], v[152:155], v[200:203], v[112:115]
	s_waitcnt lgkmcnt(1)
	v_mfma_f32_16x16x32_bf16 v[76:79], v[128:131], v[224:227], v[76:79]
	v_mfma_f32_16x16x32_bf16 v[72:75], v[152:155], v[224:227], v[72:75]
	v_mfma_f32_16x16x32_bf16 v[164:167], v[140:143], v[188:191], v[164:167]
	v_mfma_f32_16x16x32_bf16 v[160:163], v[156:159], v[188:191], v[160:163]
	v_mfma_f32_16x16x32_bf16 v[136:139], v[140:143], v[196:199], v[136:139]
	v_mfma_f32_16x16x32_bf16 v[132:135], v[156:159], v[196:199], v[132:135]
	v_mfma_f32_16x16x32_bf16 v[116:119], v[140:143], v[204:207], v[116:119]
	v_mfma_f32_16x16x32_bf16 v[112:115], v[156:159], v[204:207], v[112:115]
	s_waitcnt lgkmcnt(0)
	v_mfma_f32_16x16x32_bf16 v[76:79], v[140:143], v[228:231], v[76:79]
	v_mfma_f32_16x16x32_bf16 v[72:75], v[156:159], v[228:231], v[72:75]
	v_mfma_f32_16x16x32_bf16 v[148:151], v[168:171], v[184:187], v[148:151]
	v_mfma_f32_16x16x32_bf16 v[144:147], v[176:179], v[184:187], v[144:147]
	v_mfma_f32_16x16x32_bf16 v[124:127], v[168:171], v[192:195], v[124:127]
	v_mfma_f32_16x16x32_bf16 v[120:123], v[176:179], v[192:195], v[120:123]
	v_mfma_f32_16x16x32_bf16 v[108:111], v[168:171], v[200:203], v[108:111]
	v_mfma_f32_16x16x32_bf16 v[104:107], v[176:179], v[200:203], v[104:107]
	v_mfma_f32_16x16x32_bf16 v[68:71], v[168:171], v[224:227], v[68:71]
	v_mfma_f32_16x16x32_bf16 v[64:67], v[176:179], v[224:227], v[64:67]
	v_mfma_f32_16x16x32_bf16 v[148:151], v[172:175], v[188:191], v[148:151]
	v_mfma_f32_16x16x32_bf16 v[144:147], v[180:183], v[188:191], v[144:147]
	v_mfma_f32_16x16x32_bf16 v[124:127], v[172:175], v[196:199], v[124:127]
	v_mfma_f32_16x16x32_bf16 v[120:123], v[180:183], v[196:199], v[120:123]
	v_mfma_f32_16x16x32_bf16 v[108:111], v[172:175], v[204:207], v[108:111]
	v_mfma_f32_16x16x32_bf16 v[104:107], v[180:183], v[204:207], v[104:107]
	v_mfma_f32_16x16x32_bf16 v[68:71], v[172:175], v[228:231], v[68:71]
	v_mfma_f32_16x16x32_bf16 v[64:67], v[180:183], v[228:231], v[64:67]
	s_barrier
	ds_read_b128 v[184:187], v223 offset:16384
	ds_read_b128 v[188:191], v223 offset:17408
	ds_read_b128 v[192:195], v223 offset:18432
	ds_read_b128 v[196:199], v223 offset:19456
	ds_read_b128 v[200:203], v223 offset:20480
	ds_read_b128 v[204:207], v223 offset:21504
	ds_read_b128 v[224:227], v223 offset:22528
	ds_read_b128 v[228:231], v223 offset:23552
	s_mov_b32 m0, s51
	s_nop 0
	buffer_load_dwordx4 v220, s[52:55], s12 offen lds
	s_add_i32 s14, s12, 0x160000
	s_mov_b32 m0, s74
	s_nop 0
	buffer_load_dwordx4 v221, s[52:55], s12 offen lds
	s_mov_b32 m0, s75
	s_nop 0
	buffer_load_dwordx4 v220, s[52:55], s14 offen lds
	s_mov_b32 m0, s76
	s_nop 0
	buffer_load_dwordx4 v221, s[52:55], s14 offen lds
	s_mov_b32 m0, s31
	s_nop 0
	buffer_load_dwordx4 v220, s[20:23], s13 offen lds
	s_mov_b32 m0, s77
	s_nop 0
	buffer_load_dwordx4 v221, s[20:23], s13 offen lds
	s_waitcnt vmcnt(8)
	s_waitcnt lgkmcnt(0)
	s_barrier
	s_waitcnt lgkmcnt(7)
	v_mfma_f32_16x16x32_bf16 v[60:63], v[128:131], v[184:187], v[60:63]
	v_mfma_f32_16x16x32_bf16 v[56:59], v[152:155], v[184:187], v[56:59]
	s_waitcnt lgkmcnt(5)
	v_mfma_f32_16x16x32_bf16 v[44:47], v[128:131], v[192:195], v[44:47]
	v_mfma_f32_16x16x32_bf16 v[40:43], v[152:155], v[192:195], v[40:43]
	s_waitcnt lgkmcnt(3)
	v_mfma_f32_16x16x32_bf16 v[28:31], v[128:131], v[200:203], v[28:31]
	v_mfma_f32_16x16x32_bf16 v[24:27], v[152:155], v[200:203], v[24:27]
	s_waitcnt lgkmcnt(1)
	v_mfma_f32_16x16x32_bf16 v[12:15], v[128:131], v[224:227], v[12:15]
	v_mfma_f32_16x16x32_bf16 v[8:11], v[152:155], v[224:227], v[8:11]
	v_mfma_f32_16x16x32_bf16 v[60:63], v[140:143], v[188:191], v[60:63]
	v_mfma_f32_16x16x32_bf16 v[56:59], v[156:159], v[188:191], v[56:59]
	v_mfma_f32_16x16x32_bf16 v[44:47], v[140:143], v[196:199], v[44:47]
	v_mfma_f32_16x16x32_bf16 v[40:43], v[156:159], v[196:199], v[40:43]
	v_mfma_f32_16x16x32_bf16 v[28:31], v[140:143], v[204:207], v[28:31]
	v_mfma_f32_16x16x32_bf16 v[24:27], v[156:159], v[204:207], v[24:27]
	s_waitcnt lgkmcnt(0)
	v_mfma_f32_16x16x32_bf16 v[12:15], v[140:143], v[228:231], v[12:15]
	v_mfma_f32_16x16x32_bf16 v[8:11], v[156:159], v[228:231], v[8:11]
	v_mfma_f32_16x16x32_bf16 v[52:55], v[168:171], v[184:187], v[52:55]
	v_mfma_f32_16x16x32_bf16 v[48:51], v[176:179], v[184:187], v[48:51]
	v_mfma_f32_16x16x32_bf16 v[36:39], v[168:171], v[192:195], v[36:39]
	v_mfma_f32_16x16x32_bf16 v[32:35], v[176:179], v[192:195], v[32:35]
	v_mfma_f32_16x16x32_bf16 v[20:23], v[168:171], v[200:203], v[20:23]
	v_mfma_f32_16x16x32_bf16 v[16:19], v[176:179], v[200:203], v[16:19]
	v_mfma_f32_16x16x32_bf16 v[4:7], v[168:171], v[224:227], v[4:7]
	v_mfma_f32_16x16x32_bf16 v[0:3], v[176:179], v[224:227], v[0:3]
	v_mfma_f32_16x16x32_bf16 v[52:55], v[172:175], v[188:191], v[52:55]
	v_mfma_f32_16x16x32_bf16 v[48:51], v[180:183], v[188:191], v[48:51]
	v_mfma_f32_16x16x32_bf16 v[36:39], v[172:175], v[196:199], v[36:39]
	v_mfma_f32_16x16x32_bf16 v[32:35], v[180:183], v[196:199], v[32:35]
	v_mfma_f32_16x16x32_bf16 v[20:23], v[172:175], v[204:207], v[20:23]
	v_mfma_f32_16x16x32_bf16 v[16:19], v[180:183], v[204:207], v[16:19]
	v_mfma_f32_16x16x32_bf16 v[4:7], v[172:175], v[228:231], v[4:7]
	v_mfma_f32_16x16x32_bf16 v[0:3], v[180:183], v[228:231], v[0:3]
	s_barrier
	v_add_u32_e32 v156, 0x18000, v222
	v_add_u32_e32 v180, 0x1c000, v222
	ds_read_b128 v[128:131], v156
	ds_read_b128 v[140:143], v156 offset:1024
	ds_read_b128 v[152:155], v156 offset:2048
	ds_read_b128 v[156:159], v156 offset:3072
	ds_read_b128 v[168:171], v180
	ds_read_b128 v[172:175], v180 offset:1024
	ds_read_b128 v[176:179], v180 offset:2048
	ds_read_b128 v[180:183], v180 offset:3072
	ds_read_b128 v[184:187], v223 offset:32768
	ds_read_b128 v[188:191], v223 offset:33792
	ds_read_b128 v[192:195], v223 offset:34816
	ds_read_b128 v[196:199], v223 offset:35840
	ds_read_b128 v[200:203], v223 offset:36864
	ds_read_b128 v[204:207], v223 offset:37888
	ds_read_b128 v[224:227], v223 offset:38912
	ds_read_b128 v[228:231], v223 offset:39936
	s_add_i32 s13, s13, 0x160000
	s_mov_b32 m0, s78
	s_nop 0
	buffer_load_dwordx4 v220, s[20:23], s13 offen lds
	s_mov_b32 m0, s79
	s_nop 0
	buffer_load_dwordx4 v221, s[20:23], s13 offen lds
	s_waitcnt vmcnt(8)
	s_waitcnt lgkmcnt(0)
	s_barrier
	s_waitcnt lgkmcnt(7)
	v_mfma_f32_16x16x32_bf16 v[164:167], v[128:131], v[184:187], v[164:167]
	v_mfma_f32_16x16x32_bf16 v[160:163], v[152:155], v[184:187], v[160:163]
	s_waitcnt lgkmcnt(5)
	v_mfma_f32_16x16x32_bf16 v[136:139], v[128:131], v[192:195], v[136:139]
	v_mfma_f32_16x16x32_bf16 v[132:135], v[152:155], v[192:195], v[132:135]
	s_waitcnt lgkmcnt(3)
	v_mfma_f32_16x16x32_bf16 v[116:119], v[128:131], v[200:203], v[116:119]
	v_mfma_f32_16x16x32_bf16 v[112:115], v[152:155], v[200:203], v[112:115]
	s_waitcnt lgkmcnt(1)
	v_mfma_f32_16x16x32_bf16 v[76:79], v[128:131], v[224:227], v[76:79]
	v_mfma_f32_16x16x32_bf16 v[72:75], v[152:155], v[224:227], v[72:75]
	v_mfma_f32_16x16x32_bf16 v[164:167], v[140:143], v[188:191], v[164:167]
	v_mfma_f32_16x16x32_bf16 v[160:163], v[156:159], v[188:191], v[160:163]
	v_mfma_f32_16x16x32_bf16 v[136:139], v[140:143], v[196:199], v[136:139]
	v_mfma_f32_16x16x32_bf16 v[132:135], v[156:159], v[196:199], v[132:135]
	v_mfma_f32_16x16x32_bf16 v[116:119], v[140:143], v[204:207], v[116:119]
	v_mfma_f32_16x16x32_bf16 v[112:115], v[156:159], v[204:207], v[112:115]
	s_waitcnt lgkmcnt(0)
	v_mfma_f32_16x16x32_bf16 v[76:79], v[140:143], v[228:231], v[76:79]
	v_mfma_f32_16x16x32_bf16 v[72:75], v[156:159], v[228:231], v[72:75]
	v_mfma_f32_16x16x32_bf16 v[148:151], v[168:171], v[184:187], v[148:151]
	v_mfma_f32_16x16x32_bf16 v[144:147], v[176:179], v[184:187], v[144:147]
	v_mfma_f32_16x16x32_bf16 v[124:127], v[168:171], v[192:195], v[124:127]
	v_mfma_f32_16x16x32_bf16 v[120:123], v[176:179], v[192:195], v[120:123]
	v_mfma_f32_16x16x32_bf16 v[108:111], v[168:171], v[200:203], v[108:111]
	v_mfma_f32_16x16x32_bf16 v[104:107], v[176:179], v[200:203], v[104:107]
	v_mfma_f32_16x16x32_bf16 v[68:71], v[168:171], v[224:227], v[68:71]
	v_mfma_f32_16x16x32_bf16 v[64:67], v[176:179], v[224:227], v[64:67]
	v_mfma_f32_16x16x32_bf16 v[148:151], v[172:175], v[188:191], v[148:151]
	v_mfma_f32_16x16x32_bf16 v[144:147], v[180:183], v[188:191], v[144:147]
	v_mfma_f32_16x16x32_bf16 v[124:127], v[172:175], v[196:199], v[124:127]
	v_mfma_f32_16x16x32_bf16 v[120:123], v[180:183], v[196:199], v[120:123]
	v_mfma_f32_16x16x32_bf16 v[108:111], v[172:175], v[204:207], v[108:111]
	v_mfma_f32_16x16x32_bf16 v[104:107], v[180:183], v[204:207], v[104:107]
	v_mfma_f32_16x16x32_bf16 v[68:71], v[172:175], v[228:231], v[68:71]
	v_mfma_f32_16x16x32_bf16 v[64:67], v[180:183], v[228:231], v[64:67]
	s_barrier
	ds_read_b128 v[184:187], v223 offset:49152
	ds_read_b128 v[188:191], v223 offset:50176
	ds_read_b128 v[192:195], v223 offset:51200
	ds_read_b128 v[196:199], v223 offset:52224
	ds_read_b128 v[200:203], v223 offset:53248
	ds_read_b128 v[204:207], v223 offset:54272
	ds_read_b128 v[224:227], v223 offset:55296
	ds_read_b128 v[228:231], v223 offset:56320
	s_or_b32 s13, s12, 0x4000
	s_mov_b32 m0, s34
	s_nop 0
	buffer_load_dwordx4 v220, s[52:55], s13 offen lds
	s_add_i32 s12, s12, 0x164000
	s_mov_b32 m0, s82
	s_nop 0
	buffer_load_dwordx4 v221, s[52:55], s13 offen lds
	s_mov_b32 m0, s85
	s_nop 0
	buffer_load_dwordx4 v220, s[52:55], s12 offen lds
	s_mov_b32 m0, s86
	s_nop 0
	buffer_load_dwordx4 v221, s[52:55], s12 offen lds
	s_mov_b32 m0, s83
	s_nop 0
	buffer_load_dwordx4 v220, s[20:23], s11 offen lds
	s_mov_b32 m0, s84
	s_nop 0
	buffer_load_dwordx4 v221, s[20:23], s11 offen lds
	s_waitcnt vmcnt(8)
	s_waitcnt lgkmcnt(0)
	s_barrier
	s_waitcnt lgkmcnt(7)
	v_mfma_f32_16x16x32_bf16 v[60:63], v[128:131], v[184:187], v[60:63]
	v_mfma_f32_16x16x32_bf16 v[56:59], v[152:155], v[184:187], v[56:59]
	s_waitcnt lgkmcnt(5)
	v_mfma_f32_16x16x32_bf16 v[44:47], v[128:131], v[192:195], v[44:47]
	v_mfma_f32_16x16x32_bf16 v[40:43], v[152:155], v[192:195], v[40:43]
	s_waitcnt lgkmcnt(3)
	v_mfma_f32_16x16x32_bf16 v[28:31], v[128:131], v[200:203], v[28:31]
	v_mfma_f32_16x16x32_bf16 v[24:27], v[152:155], v[200:203], v[24:27]
	s_waitcnt lgkmcnt(1)
	v_mfma_f32_16x16x32_bf16 v[12:15], v[128:131], v[224:227], v[12:15]
	v_mfma_f32_16x16x32_bf16 v[8:11], v[152:155], v[224:227], v[8:11]
	v_mfma_f32_16x16x32_bf16 v[60:63], v[140:143], v[188:191], v[60:63]
	v_mfma_f32_16x16x32_bf16 v[56:59], v[156:159], v[188:191], v[56:59]
	v_mfma_f32_16x16x32_bf16 v[44:47], v[140:143], v[196:199], v[44:47]
	v_mfma_f32_16x16x32_bf16 v[40:43], v[156:159], v[196:199], v[40:43]
	v_mfma_f32_16x16x32_bf16 v[28:31], v[140:143], v[204:207], v[28:31]
	v_mfma_f32_16x16x32_bf16 v[24:27], v[156:159], v[204:207], v[24:27]
	s_waitcnt lgkmcnt(0)
	v_mfma_f32_16x16x32_bf16 v[12:15], v[140:143], v[228:231], v[12:15]
	v_mfma_f32_16x16x32_bf16 v[8:11], v[156:159], v[228:231], v[8:11]
	v_mfma_f32_16x16x32_bf16 v[52:55], v[168:171], v[184:187], v[52:55]
	v_mfma_f32_16x16x32_bf16 v[48:51], v[176:179], v[184:187], v[48:51]
	v_mfma_f32_16x16x32_bf16 v[36:39], v[168:171], v[192:195], v[36:39]
	v_mfma_f32_16x16x32_bf16 v[32:35], v[176:179], v[192:195], v[32:35]
	v_mfma_f32_16x16x32_bf16 v[20:23], v[168:171], v[200:203], v[20:23]
	v_mfma_f32_16x16x32_bf16 v[16:19], v[176:179], v[200:203], v[16:19]
	v_mfma_f32_16x16x32_bf16 v[4:7], v[168:171], v[224:227], v[4:7]
	v_mfma_f32_16x16x32_bf16 v[0:3], v[176:179], v[224:227], v[0:3]
	v_mfma_f32_16x16x32_bf16 v[52:55], v[172:175], v[188:191], v[52:55]
	v_mfma_f32_16x16x32_bf16 v[48:51], v[180:183], v[188:191], v[48:51]
	v_mfma_f32_16x16x32_bf16 v[36:39], v[172:175], v[196:199], v[36:39]
	v_mfma_f32_16x16x32_bf16 v[32:35], v[180:183], v[196:199], v[32:35]
	v_mfma_f32_16x16x32_bf16 v[20:23], v[172:175], v[204:207], v[20:23]
	v_mfma_f32_16x16x32_bf16 v[16:19], v[180:183], v[204:207], v[16:19]
	v_mfma_f32_16x16x32_bf16 v[4:7], v[172:175], v[228:231], v[4:7]
	v_mfma_f32_16x16x32_bf16 v[0:3], v[180:183], v[228:231], v[0:3]
	s_barrier
	s_add_i32 s10, s10, 2
	s_add_i32 s8, s8, 0x8000
	s_add_i32 s9, s9, 0x8000
	s_cmpk_gt_u32 s10, 0x55
	s_cbranch_scc0 .LBB0_885
